# nt cache policy on the read-once K/V row streams of the sample attention items
# baseline (speedup 1.0000x reference)
.LBB0_682:
	s_add_i32 s2, s33, 0x500
	s_and_b32 s4, s2, 0x7ff
	s_and_b64 s[2:3], s[86:87], exec
	s_cselect_b32 s56, s4, s33
	s_cmpk_gt_i32 s56, 0x2ff
	s_mov_b64 s[2:3], -1
	s_cbranch_scc0 .LBB0_734
	s_cmpk_gt_u32 s56, 0x4ff
	s_cbranch_scc0 .LBB0_731
	s_cmpk_gt_u32 s56, 0x57f
	s_cbranch_scc0 .LBB0_726
	s_cmpk_gt_u32 s56, 0x67f
	s_cbranch_scc0 .LBB0_709
	s_cmpk_lt_u32 s56, 0x780
	s_cbranch_scc1 .LBB0_696
	v_and_b32_e32 v18, 63, v208
	v_lshrrev_b32_e32 v19, 6, v208
	v_and_b32_e32 v20, 3, v19
	v_lshrrev_b32_e32 v21, 2, v19
	v_and_b32_e32 v22, 15, v18
	v_lshrrev_b32_e32 v23, 4, v18
	v_lshlrev_b32_e32 v176, 2, v18
	v_xor_b32_e32 v238, 64, v176
	v_xor_b32_e32 v239, 0x80, v176
	s_and_b32 s2, s56, 0x7c
	s_and_b32 s94, s56, 3
	v_readfirstlane_b32 s6, v21
	v_add_u32_e32 v230, s2, v20
	v_or_b32_e32 v230, 0x2000, v230
	v_mul_u32_u24_e32 v231, 0x5800, v230
	s_lshl_b32 s3, s94, 8
	v_lshl_add_u32 v232, v22, 4, v231
	v_add_u32_e32 v232, s3, v232
	v_add_u32_e32 v232, 0x5000, v232
	global_load_dwordx4 v[160:163], v232, s[0:1]
	v_add_u32_e32 v232, 0x400, v232
	v_mov_b32_e32 v233, 0
	v_lshl_add_u64 v[244:245], s[0:1], 0, v[232:233]
	v_mul_u32_u24_e32 v231, 0x1c00, v230
	v_lshl_add_u32 v232, v22, 4, v231
	v_add_u32_e32 v232, s3, v232
	v_add_u32_e32 v232, 0x1d301800, v232
	v_lshl_add_u64 v[246:247], s[96:97], 0, v[232:233]
	s_lshl_b32 s7, s2, 17
	s_lshl_b32 s8, s94, 9
	s_lshl_b32 s6, s6, 18
	s_add_u32 s7, s7, s8
	s_add_u32 s7, s7, s6
	s_add_u32 s2, s70, s7
	s_addc_u32 s3, s71, 0
	s_add_u32 s4, s72, s7
	s_addc_u32 s5, s73, 0
	v_lshlrev_b32_e32 v24, 15, v23
	v_lshl_add_u32 v24, v22, 5, v24
	v_add_u32_e32 v25, 0x1000, v24
	v_add_u32_e32 v26, 0x2000, v24
	v_add_u32_e32 v27, 0x3000, v24
	v_add_u32_e32 v28, 0x4000, v24
	v_add_u32_e32 v29, 0x5000, v24
	v_add_u32_e32 v30, 0x6000, v24
	v_add_u32_e32 v31, 0x7000, v24
	v_mov_b32_e32 v16, v206
	v_mov_b32_e32 v17, 0
	v_mov_b32_e32 v8, 0
	v_mov_b32_e32 v9, 0
	v_mov_b32_e32 v10, 0
	v_mov_b32_e32 v11, 0
	v_mov_b32_e32 v12, 0
	v_mov_b32_e32 v13, 0
	v_mov_b32_e32 v14, 0
	v_mov_b32_e32 v15, 0
	global_load_dwordx4 v[32:35], v24, s[2:3] nt
	global_load_dwordx4 v[36:39], v24, s[2:3] offset:16 nt
	global_load_dwordx4 v[40:43], v24, s[2:3] offset:2048 nt
	global_load_dwordx4 v[44:47], v24, s[2:3] offset:2064 nt
	global_load_dwordx4 v[48:51], v25, s[2:3] nt
	global_load_dwordx4 v[52:55], v25, s[2:3] offset:16 nt
	global_load_dwordx4 v[56:59], v25, s[2:3] offset:2048 nt
	global_load_dwordx4 v[60:63], v25, s[2:3] offset:2064 nt
	global_load_dwordx4 v[64:67], v26, s[2:3] nt
	global_load_dwordx4 v[68:71], v26, s[2:3] offset:16 nt
	global_load_dwordx4 v[72:75], v26, s[2:3] offset:2048 nt
	global_load_dwordx4 v[76:79], v26, s[2:3] offset:2064 nt
	global_load_dwordx4 v[80:83], v27, s[2:3] nt
	global_load_dwordx4 v[84:87], v27, s[2:3] offset:16 nt
	global_load_dwordx4 v[88:91], v27, s[2:3] offset:2048 nt
	global_load_dwordx4 v[92:95], v27, s[2:3] offset:2064 nt
	global_load_dwordx4 v[96:99], v28, s[2:3] nt
	global_load_dwordx4 v[100:103], v28, s[2:3] offset:16 nt
	global_load_dwordx4 v[104:107], v28, s[2:3] offset:2048 nt
	global_load_dwordx4 v[108:111], v28, s[2:3] offset:2064 nt
	global_load_dwordx4 v[112:115], v29, s[2:3] nt
	global_load_dwordx4 v[116:119], v29, s[2:3] offset:16 nt
	global_load_dwordx4 v[120:123], v29, s[2:3] offset:2048 nt
	global_load_dwordx4 v[124:127], v29, s[2:3] offset:2064 nt
	global_load_dwordx4 v[128:131], v30, s[2:3] nt
	global_load_dwordx4 v[132:135], v30, s[2:3] offset:16 nt
	global_load_dwordx4 v[136:139], v30, s[2:3] offset:2048 nt
	global_load_dwordx4 v[140:143], v30, s[2:3] offset:2064 nt
	global_load_dwordx4 v[144:147], v31, s[2:3] nt
	global_load_dwordx4 v[148:151], v31, s[2:3] offset:16 nt
	global_load_dwordx4 v[152:155], v31, s[2:3] offset:2048 nt
	global_load_dwordx4 v[156:159], v31, s[2:3] offset:2064 nt
	s_waitcnt vmcnt(32)
	v_lshlrev_b32_e32 v0, 16, v160
	v_and_b32_e32 v1, 0xffff0000, v160
	v_lshlrev_b32_e32 v2, 16, v161
	v_and_b32_e32 v3, 0xffff0000, v161
	v_lshlrev_b32_e32 v4, 16, v162
	v_and_b32_e32 v5, 0xffff0000, v162
	v_lshlrev_b32_e32 v6, 16, v163
	v_and_b32_e32 v7, 0xffff0000, v163
	s_waitcnt vmcnt(30)
	v_mul_f32_e32 v160, v32, v0
	v_fmac_f32_e32 v160, v33, v1
	v_fmac_f32_e32 v160, v34, v2
	v_fmac_f32_e32 v160, v35, v3
	v_fmac_f32_e32 v160, v36, v4
	v_fmac_f32_e32 v160, v37, v5
	v_fmac_f32_e32 v160, v38, v6
	v_fmac_f32_e32 v160, v39, v7
	global_load_dwordx4 v[32:35], v24, s[4:5] nt
	global_load_dwordx4 v[36:39], v24, s[4:5] offset:16 nt
	s_waitcnt vmcnt(30)
	v_mul_f32_e32 v161, v40, v0
	v_fmac_f32_e32 v161, v41, v1
	v_fmac_f32_e32 v161, v42, v2
	v_fmac_f32_e32 v161, v43, v3
	v_fmac_f32_e32 v161, v44, v4
	v_fmac_f32_e32 v161, v45, v5
	v_fmac_f32_e32 v161, v46, v6
	v_fmac_f32_e32 v161, v47, v7
	global_load_dwordx4 v[40:43], v24, s[4:5] offset:2048 nt
	global_load_dwordx4 v[44:47], v24, s[4:5] offset:2064 nt
	s_waitcnt vmcnt(30)
	v_mul_f32_e32 v162, v48, v0
	v_fmac_f32_e32 v162, v49, v1
	v_fmac_f32_e32 v162, v50, v2
	v_fmac_f32_e32 v162, v51, v3
	v_fmac_f32_e32 v162, v52, v4
	v_fmac_f32_e32 v162, v53, v5
	v_fmac_f32_e32 v162, v54, v6
	v_fmac_f32_e32 v162, v55, v7
	global_load_dwordx4 v[48:51], v25, s[4:5] nt
	global_load_dwordx4 v[52:55], v25, s[4:5] offset:16 nt
	s_waitcnt vmcnt(30)
	v_mul_f32_e32 v163, v56, v0
	v_fmac_f32_e32 v163, v57, v1
	v_fmac_f32_e32 v163, v58, v2
	v_fmac_f32_e32 v163, v59, v3
	v_fmac_f32_e32 v163, v60, v4
	v_fmac_f32_e32 v163, v61, v5
	v_fmac_f32_e32 v163, v62, v6
	v_fmac_f32_e32 v163, v63, v7
	global_load_dwordx4 v[56:59], v25, s[4:5] offset:2048 nt
	global_load_dwordx4 v[60:63], v25, s[4:5] offset:2064 nt
	s_waitcnt vmcnt(30)
	v_mul_f32_e32 v164, v64, v0
	v_fmac_f32_e32 v164, v65, v1
	v_fmac_f32_e32 v164, v66, v2
	v_fmac_f32_e32 v164, v67, v3
	v_fmac_f32_e32 v164, v68, v4
	v_fmac_f32_e32 v164, v69, v5
	v_fmac_f32_e32 v164, v70, v6
	v_fmac_f32_e32 v164, v71, v7
	global_load_dwordx4 v[64:67], v26, s[4:5] nt
	global_load_dwordx4 v[68:71], v26, s[4:5] offset:16 nt
	s_waitcnt vmcnt(30)
	v_mul_f32_e32 v165, v72, v0
	v_fmac_f32_e32 v165, v73, v1
	v_fmac_f32_e32 v165, v74, v2
	v_fmac_f32_e32 v165, v75, v3
	v_fmac_f32_e32 v165, v76, v4
	v_fmac_f32_e32 v165, v77, v5
	v_fmac_f32_e32 v165, v78, v6
	v_fmac_f32_e32 v165, v79, v7
	global_load_dwordx4 v[72:75], v26, s[4:5] offset:2048 nt
	global_load_dwordx4 v[76:79], v26, s[4:5] offset:2064 nt
	s_waitcnt vmcnt(30)
	v_mul_f32_e32 v166, v80, v0
	v_fmac_f32_e32 v166, v81, v1
	v_fmac_f32_e32 v166, v82, v2
	v_fmac_f32_e32 v166, v83, v3
	v_fmac_f32_e32 v166, v84, v4
	v_fmac_f32_e32 v166, v85, v5
	v_fmac_f32_e32 v166, v86, v6
	v_fmac_f32_e32 v166, v87, v7
	global_load_dwordx4 v[80:83], v27, s[4:5] nt
	global_load_dwordx4 v[84:87], v27, s[4:5] offset:16 nt
	s_waitcnt vmcnt(30)
	v_mul_f32_e32 v167, v88, v0
	v_fmac_f32_e32 v167, v89, v1
	v_fmac_f32_e32 v167, v90, v2
	v_fmac_f32_e32 v167, v91, v3
	v_fmac_f32_e32 v167, v92, v4
	v_fmac_f32_e32 v167, v93, v5
	v_fmac_f32_e32 v167, v94, v6
	v_fmac_f32_e32 v167, v95, v7
	global_load_dwordx4 v[88:91], v27, s[4:5] offset:2048 nt
	global_load_dwordx4 v[92:95], v27, s[4:5] offset:2064 nt
	s_waitcnt vmcnt(30)
	v_mul_f32_e32 v168, v96, v0
	v_fmac_f32_e32 v168, v97, v1
	v_fmac_f32_e32 v168, v98, v2
	v_fmac_f32_e32 v168, v99, v3
	v_fmac_f32_e32 v168, v100, v4
	v_fmac_f32_e32 v168, v101, v5
	v_fmac_f32_e32 v168, v102, v6
	v_fmac_f32_e32 v168, v103, v7
	global_load_dwordx4 v[96:99], v28, s[4:5] nt
	global_load_dwordx4 v[100:103], v28, s[4:5] offset:16 nt
	s_waitcnt vmcnt(30)
	v_mul_f32_e32 v169, v104, v0
	v_fmac_f32_e32 v169, v105, v1
	v_fmac_f32_e32 v169, v106, v2
	v_fmac_f32_e32 v169, v107, v3
	v_fmac_f32_e32 v169, v108, v4
	v_fmac_f32_e32 v169, v109, v5
	v_fmac_f32_e32 v169, v110, v6
	v_fmac_f32_e32 v169, v111, v7
	global_load_dwordx4 v[104:107], v28, s[4:5] offset:2048 nt
	global_load_dwordx4 v[108:111], v28, s[4:5] offset:2064 nt
	s_waitcnt vmcnt(30)
	v_mul_f32_e32 v170, v112, v0
	v_fmac_f32_e32 v170, v113, v1
	v_fmac_f32_e32 v170, v114, v2
	v_fmac_f32_e32 v170, v115, v3
	v_fmac_f32_e32 v170, v116, v4
	v_fmac_f32_e32 v170, v117, v5
	v_fmac_f32_e32 v170, v118, v6
	v_fmac_f32_e32 v170, v119, v7
	global_load_dwordx4 v[112:115], v29, s[4:5] nt
	global_load_dwordx4 v[116:119], v29, s[4:5] offset:16 nt
	s_waitcnt vmcnt(30)
	v_mul_f32_e32 v171, v120, v0
	v_fmac_f32_e32 v171, v121, v1
	v_fmac_f32_e32 v171, v122, v2
	v_fmac_f32_e32 v171, v123, v3
	v_fmac_f32_e32 v171, v124, v4
	v_fmac_f32_e32 v171, v125, v5
	v_fmac_f32_e32 v171, v126, v6
	v_fmac_f32_e32 v171, v127, v7
	global_load_dwordx4 v[120:123], v29, s[4:5] offset:2048 nt
	global_load_dwordx4 v[124:127], v29, s[4:5] offset:2064 nt
	s_waitcnt vmcnt(30)
	v_mul_f32_e32 v172, v128, v0
	v_fmac_f32_e32 v172, v129, v1
	v_fmac_f32_e32 v172, v130, v2
	v_fmac_f32_e32 v172, v131, v3
	v_fmac_f32_e32 v172, v132, v4
	v_fmac_f32_e32 v172, v133, v5
	v_fmac_f32_e32 v172, v134, v6
	v_fmac_f32_e32 v172, v135, v7
	global_load_dwordx4 v[128:131], v30, s[4:5] nt
	global_load_dwordx4 v[132:135], v30, s[4:5] offset:16 nt
	s_waitcnt vmcnt(30)
	v_mul_f32_e32 v173, v136, v0
	v_fmac_f32_e32 v173, v137, v1
	v_fmac_f32_e32 v173, v138, v2
	v_fmac_f32_e32 v173, v139, v3
	v_fmac_f32_e32 v173, v140, v4
	v_fmac_f32_e32 v173, v141, v5
	v_fmac_f32_e32 v173, v142, v6
	v_fmac_f32_e32 v173, v143, v7
	global_load_dwordx4 v[136:139], v30, s[4:5] offset:2048 nt
	global_load_dwordx4 v[140:143], v30, s[4:5] offset:2064 nt
	s_waitcnt vmcnt(30)
	v_mul_f32_e32 v174, v144, v0
	v_fmac_f32_e32 v174, v145, v1
	v_fmac_f32_e32 v174, v146, v2
	v_fmac_f32_e32 v174, v147, v3
	v_fmac_f32_e32 v174, v148, v4
	v_fmac_f32_e32 v174, v149, v5
	v_fmac_f32_e32 v174, v150, v6
	v_fmac_f32_e32 v174, v151, v7
	global_load_dwordx4 v[144:147], v31, s[4:5] nt
	global_load_dwordx4 v[148:151], v31, s[4:5] offset:16 nt
	s_waitcnt vmcnt(30)
	v_mul_f32_e32 v175, v152, v0
	v_fmac_f32_e32 v175, v153, v1
	v_fmac_f32_e32 v175, v154, v2
	v_fmac_f32_e32 v175, v155, v3
	v_fmac_f32_e32 v175, v156, v4
	v_fmac_f32_e32 v175, v157, v5
	v_fmac_f32_e32 v175, v158, v6
	v_fmac_f32_e32 v175, v159, v7
	global_load_dwordx4 v[152:155], v31, s[4:5] offset:2048 nt
	global_load_dwordx4 v[156:159], v31, s[4:5] offset:2064 nt
	v_add_f32_dpp v160, v160, v160 row_ror:8 row_mask:0xf bank_mask:0x3
	v_add_f32_dpp v160, v168, v168 row_ror:8 row_mask:0xf bank_mask:0xc
	v_add_f32_dpp v161, v161, v161 row_ror:8 row_mask:0xf bank_mask:0x3
	v_add_f32_dpp v161, v169, v169 row_ror:8 row_mask:0xf bank_mask:0xc
	v_add_f32_dpp v162, v162, v162 row_ror:8 row_mask:0xf bank_mask:0x3
	v_add_f32_dpp v162, v170, v170 row_ror:8 row_mask:0xf bank_mask:0xc
	v_add_f32_dpp v163, v163, v163 row_ror:8 row_mask:0xf bank_mask:0x3
	v_add_f32_dpp v163, v171, v171 row_ror:8 row_mask:0xf bank_mask:0xc
	v_add_f32_dpp v164, v164, v164 row_ror:8 row_mask:0xf bank_mask:0x3
	v_add_f32_dpp v164, v172, v172 row_ror:8 row_mask:0xf bank_mask:0xc
	v_add_f32_dpp v165, v165, v165 row_ror:8 row_mask:0xf bank_mask:0x3
	v_add_f32_dpp v165, v173, v173 row_ror:8 row_mask:0xf bank_mask:0xc
	v_add_f32_dpp v166, v166, v166 row_ror:8 row_mask:0xf bank_mask:0x3
	v_add_f32_dpp v166, v174, v174 row_ror:8 row_mask:0xf bank_mask:0xc
	v_add_f32_dpp v167, v167, v167 row_ror:8 row_mask:0xf bank_mask:0x3
	v_add_f32_dpp v167, v175, v175 row_ror:8 row_mask:0xf bank_mask:0xc
	v_add_f32_dpp v160, v160, v160 row_shl:4 row_mask:0xf bank_mask:0x5
	v_add_f32_dpp v160, v164, v164 row_shr:4 row_mask:0xf bank_mask:0xa
	v_add_f32_dpp v161, v161, v161 row_shl:4 row_mask:0xf bank_mask:0x5
	v_add_f32_dpp v161, v165, v165 row_shr:4 row_mask:0xf bank_mask:0xa
	v_add_f32_dpp v162, v162, v162 row_shl:4 row_mask:0xf bank_mask:0x5
	v_add_f32_dpp v162, v166, v166 row_shr:4 row_mask:0xf bank_mask:0xa
	v_add_f32_dpp v163, v163, v163 row_shl:4 row_mask:0xf bank_mask:0x5
	v_add_f32_dpp v163, v167, v167 row_shr:4 row_mask:0xf bank_mask:0xa
	v_and_b32_e32 v176, 2, v18
	v_cmp_ne_u32_e32 vcc, 0, v176
	v_add_f32_dpp v230, v160, v160 quad_perm:[2,3,0,1] row_mask:0xf bank_mask:0xf
	v_add_f32_dpp v231, v162, v162 quad_perm:[2,3,0,1] row_mask:0xf bank_mask:0xf
	v_add_f32_dpp v232, v161, v161 quad_perm:[2,3,0,1] row_mask:0xf bank_mask:0xf
	v_add_f32_dpp v233, v163, v163 quad_perm:[2,3,0,1] row_mask:0xf bank_mask:0xf
	v_cndmask_b32_e32 v230, v230, v231, vcc
	v_cndmask_b32_e32 v232, v232, v233, vcc
	v_and_b32_e32 v176, 1, v18
	v_cmp_ne_u32_e32 vcc, 0, v176
	v_add_f32_dpp v231, v230, v230 quad_perm:[1,0,3,2] row_mask:0xf bank_mask:0xf
	v_add_f32_dpp v233, v232, v232 quad_perm:[1,0,3,2] row_mask:0xf bank_mask:0xf
	s_nop 1
	v_cndmask_b32_e32 v241, v231, v233, vcc
	s_nop 1
	v_max_f32_dpp v242, v241, v241 row_ror:8 row_mask:0xf bank_mask:0xf
	s_nop 1
	v_max_f32_dpp v242, v242, v242 row_ror:4 row_mask:0xf bank_mask:0xf
	s_nop 1
	v_max_f32_dpp v242, v242, v242 row_ror:2 row_mask:0xf bank_mask:0xf
	s_nop 1
	v_max_f32_dpp v242, v242, v242 row_ror:1 row_mask:0xf bank_mask:0xf
	ds_bpermute_b32 v234, v238, v242
	s_waitcnt lgkmcnt(0)
	v_max_f32_e32 v242, v242, v234
	ds_bpermute_b32 v234, v239, v242
	s_waitcnt lgkmcnt(0)
	v_max_f32_e32 v242, v242, v234
	v_max_f32_e32 v242, v16, v242
	v_sub_f32_e32 v243, v16, v242
	v_sub_f32_e32 v240, v241, v242
	v_mul_f32_e32 v243, 0x3fb8aa3b, v243
	v_mul_f32_e32 v240, 0x3fb8aa3b, v240
	v_exp_f32_e32 v243, v243
	v_exp_f32_e32 v240, v240
	v_mov_b32_e32 v16, v242
	s_nop 0
	s_nop 1
	v_add_f32_dpp v235, v240, v240 row_ror:8 row_mask:0xf bank_mask:0xf
	s_nop 1
	v_add_f32_dpp v235, v235, v235 row_ror:4 row_mask:0xf bank_mask:0xf
	s_nop 1
	v_add_f32_dpp v235, v235, v235 row_ror:2 row_mask:0xf bank_mask:0xf
	s_nop 1
	v_add_f32_dpp v235, v235, v235 row_ror:1 row_mask:0xf bank_mask:0xf
	ds_bpermute_b32 v234, v238, v235
	s_waitcnt lgkmcnt(0)
	v_add_f32_e32 v235, v235, v234
	ds_bpermute_b32 v234, v239, v235
	s_waitcnt lgkmcnt(0)
	v_add_f32_e32 v235, v235, v234
	v_fma_f32 v17, v17, v243, v235
	v_mul_f32_e32 v8, v8, v243
	v_mul_f32_e32 v9, v9, v243
	v_mul_f32_e32 v10, v10, v243
	v_mul_f32_e32 v11, v11, v243
	v_mul_f32_e32 v12, v12, v243
	v_mul_f32_e32 v13, v13, v243
	v_mul_f32_e32 v14, v14, v243
	v_mul_f32_e32 v15, v15, v243
	s_add_u32 s2, s2, 0x20000
	s_addc_u32 s3, s3, 0
	s_add_u32 s4, s4, 0x20000
	s_addc_u32 s5, s5, 0
	s_waitcnt vmcnt(30)
	v_fmac_f32_dpp v8, v240, v32 row_newbcast:0 row_mask:0xf bank_mask:0xf
	v_fmac_f32_dpp v9, v240, v33 row_newbcast:0 row_mask:0xf bank_mask:0xf
	v_fmac_f32_dpp v10, v240, v34 row_newbcast:0 row_mask:0xf bank_mask:0xf
	v_fmac_f32_dpp v11, v240, v35 row_newbcast:0 row_mask:0xf bank_mask:0xf
	v_fmac_f32_dpp v12, v240, v36 row_newbcast:0 row_mask:0xf bank_mask:0xf
	v_fmac_f32_dpp v13, v240, v37 row_newbcast:0 row_mask:0xf bank_mask:0xf
	v_fmac_f32_dpp v14, v240, v38 row_newbcast:0 row_mask:0xf bank_mask:0xf
	v_fmac_f32_dpp v15, v240, v39 row_newbcast:0 row_mask:0xf bank_mask:0xf
	global_load_dwordx4 v[32:35], v24, s[2:3] nt
	global_load_dwordx4 v[36:39], v24, s[2:3] offset:16 nt
	s_waitcnt vmcnt(30)
	v_fmac_f32_dpp v8, v240, v40 row_newbcast:1 row_mask:0xf bank_mask:0xf
	v_fmac_f32_dpp v9, v240, v41 row_newbcast:1 row_mask:0xf bank_mask:0xf
	v_fmac_f32_dpp v10, v240, v42 row_newbcast:1 row_mask:0xf bank_mask:0xf
	v_fmac_f32_dpp v11, v240, v43 row_newbcast:1 row_mask:0xf bank_mask:0xf
	v_fmac_f32_dpp v12, v240, v44 row_newbcast:1 row_mask:0xf bank_mask:0xf
	v_fmac_f32_dpp v13, v240, v45 row_newbcast:1 row_mask:0xf bank_mask:0xf
	v_fmac_f32_dpp v14, v240, v46 row_newbcast:1 row_mask:0xf bank_mask:0xf
	v_fmac_f32_dpp v15, v240, v47 row_newbcast:1 row_mask:0xf bank_mask:0xf
	global_load_dwordx4 v[40:43], v24, s[2:3] offset:2048 nt
	global_load_dwordx4 v[44:47], v24, s[2:3] offset:2064 nt
	s_waitcnt vmcnt(30)
	v_fmac_f32_dpp v8, v240, v48 row_newbcast:2 row_mask:0xf bank_mask:0xf
	v_fmac_f32_dpp v9, v240, v49 row_newbcast:2 row_mask:0xf bank_mask:0xf
	v_fmac_f32_dpp v10, v240, v50 row_newbcast:2 row_mask:0xf bank_mask:0xf
	v_fmac_f32_dpp v11, v240, v51 row_newbcast:2 row_mask:0xf bank_mask:0xf
	v_fmac_f32_dpp v12, v240, v52 row_newbcast:2 row_mask:0xf bank_mask:0xf
	v_fmac_f32_dpp v13, v240, v53 row_newbcast:2 row_mask:0xf bank_mask:0xf
	v_fmac_f32_dpp v14, v240, v54 row_newbcast:2 row_mask:0xf bank_mask:0xf
	v_fmac_f32_dpp v15, v240, v55 row_newbcast:2 row_mask:0xf bank_mask:0xf
	global_load_dwordx4 v[48:51], v25, s[2:3] nt
	global_load_dwordx4 v[52:55], v25, s[2:3] offset:16 nt
	s_waitcnt vmcnt(30)
	v_fmac_f32_dpp v8, v240, v56 row_newbcast:3 row_mask:0xf bank_mask:0xf
	v_fmac_f32_dpp v9, v240, v57 row_newbcast:3 row_mask:0xf bank_mask:0xf
	v_fmac_f32_dpp v10, v240, v58 row_newbcast:3 row_mask:0xf bank_mask:0xf
	v_fmac_f32_dpp v11, v240, v59 row_newbcast:3 row_mask:0xf bank_mask:0xf
	v_fmac_f32_dpp v12, v240, v60 row_newbcast:3 row_mask:0xf bank_mask:0xf
	v_fmac_f32_dpp v13, v240, v61 row_newbcast:3 row_mask:0xf bank_mask:0xf
	v_fmac_f32_dpp v14, v240, v62 row_newbcast:3 row_mask:0xf bank_mask:0xf
	v_fmac_f32_dpp v15, v240, v63 row_newbcast:3 row_mask:0xf bank_mask:0xf
	global_load_dwordx4 v[56:59], v25, s[2:3] offset:2048 nt
	global_load_dwordx4 v[60:63], v25, s[2:3] offset:2064 nt
	s_waitcnt vmcnt(30)
	v_fmac_f32_dpp v8, v240, v64 row_newbcast:4 row_mask:0xf bank_mask:0xf
	v_fmac_f32_dpp v9, v240, v65 row_newbcast:4 row_mask:0xf bank_mask:0xf
	v_fmac_f32_dpp v10, v240, v66 row_newbcast:4 row_mask:0xf bank_mask:0xf
	v_fmac_f32_dpp v11, v240, v67 row_newbcast:4 row_mask:0xf bank_mask:0xf
	v_fmac_f32_dpp v12, v240, v68 row_newbcast:4 row_mask:0xf bank_mask:0xf
	v_fmac_f32_dpp v13, v240, v69 row_newbcast:4 row_mask:0xf bank_mask:0xf
	v_fmac_f32_dpp v14, v240, v70 row_newbcast:4 row_mask:0xf bank_mask:0xf
	v_fmac_f32_dpp v15, v240, v71 row_newbcast:4 row_mask:0xf bank_mask:0xf
	global_load_dwordx4 v[64:67], v26, s[2:3] nt
	global_load_dwordx4 v[68:71], v26, s[2:3] offset:16 nt
	s_waitcnt vmcnt(30)
	v_fmac_f32_dpp v8, v240, v72 row_newbcast:5 row_mask:0xf bank_mask:0xf
	v_fmac_f32_dpp v9, v240, v73 row_newbcast:5 row_mask:0xf bank_mask:0xf
	v_fmac_f32_dpp v10, v240, v74 row_newbcast:5 row_mask:0xf bank_mask:0xf
	v_fmac_f32_dpp v11, v240, v75 row_newbcast:5 row_mask:0xf bank_mask:0xf
	v_fmac_f32_dpp v12, v240, v76 row_newbcast:5 row_mask:0xf bank_mask:0xf
	v_fmac_f32_dpp v13, v240, v77 row_newbcast:5 row_mask:0xf bank_mask:0xf
	v_fmac_f32_dpp v14, v240, v78 row_newbcast:5 row_mask:0xf bank_mask:0xf
	v_fmac_f32_dpp v15, v240, v79 row_newbcast:5 row_mask:0xf bank_mask:0xf
	global_load_dwordx4 v[72:75], v26, s[2:3] offset:2048 nt
	global_load_dwordx4 v[76:79], v26, s[2:3] offset:2064 nt
	s_waitcnt vmcnt(30)
	v_fmac_f32_dpp v8, v240, v80 row_newbcast:6 row_mask:0xf bank_mask:0xf
	v_fmac_f32_dpp v9, v240, v81 row_newbcast:6 row_mask:0xf bank_mask:0xf
	v_fmac_f32_dpp v10, v240, v82 row_newbcast:6 row_mask:0xf bank_mask:0xf
	v_fmac_f32_dpp v11, v240, v83 row_newbcast:6 row_mask:0xf bank_mask:0xf
	v_fmac_f32_dpp v12, v240, v84 row_newbcast:6 row_mask:0xf bank_mask:0xf
	v_fmac_f32_dpp v13, v240, v85 row_newbcast:6 row_mask:0xf bank_mask:0xf
	v_fmac_f32_dpp v14, v240, v86 row_newbcast:6 row_mask:0xf bank_mask:0xf
	v_fmac_f32_dpp v15, v240, v87 row_newbcast:6 row_mask:0xf bank_mask:0xf
	global_load_dwordx4 v[80:83], v27, s[2:3] nt
	global_load_dwordx4 v[84:87], v27, s[2:3] offset:16 nt
	s_waitcnt vmcnt(30)
	v_fmac_f32_dpp v8, v240, v88 row_newbcast:7 row_mask:0xf bank_mask:0xf
	v_fmac_f32_dpp v9, v240, v89 row_newbcast:7 row_mask:0xf bank_mask:0xf
	v_fmac_f32_dpp v10, v240, v90 row_newbcast:7 row_mask:0xf bank_mask:0xf
	v_fmac_f32_dpp v11, v240, v91 row_newbcast:7 row_mask:0xf bank_mask:0xf
	v_fmac_f32_dpp v12, v240, v92 row_newbcast:7 row_mask:0xf bank_mask:0xf
	v_fmac_f32_dpp v13, v240, v93 row_newbcast:7 row_mask:0xf bank_mask:0xf
	v_fmac_f32_dpp v14, v240, v94 row_newbcast:7 row_mask:0xf bank_mask:0xf
	v_fmac_f32_dpp v15, v240, v95 row_newbcast:7 row_mask:0xf bank_mask:0xf
	global_load_dwordx4 v[88:91], v27, s[2:3] offset:2048 nt
	global_load_dwordx4 v[92:95], v27, s[2:3] offset:2064 nt
	s_waitcnt vmcnt(30)
	v_fmac_f32_dpp v8, v240, v96 row_newbcast:8 row_mask:0xf bank_mask:0xf
	v_fmac_f32_dpp v9, v240, v97 row_newbcast:8 row_mask:0xf bank_mask:0xf
	v_fmac_f32_dpp v10, v240, v98 row_newbcast:8 row_mask:0xf bank_mask:0xf
	v_fmac_f32_dpp v11, v240, v99 row_newbcast:8 row_mask:0xf bank_mask:0xf
	v_fmac_f32_dpp v12, v240, v100 row_newbcast:8 row_mask:0xf bank_mask:0xf
	v_fmac_f32_dpp v13, v240, v101 row_newbcast:8 row_mask:0xf bank_mask:0xf
	v_fmac_f32_dpp v14, v240, v102 row_newbcast:8 row_mask:0xf bank_mask:0xf
	v_fmac_f32_dpp v15, v240, v103 row_newbcast:8 row_mask:0xf bank_mask:0xf
	global_load_dwordx4 v[96:99], v28, s[2:3] nt
	global_load_dwordx4 v[100:103], v28, s[2:3] offset:16 nt
	s_waitcnt vmcnt(30)
	v_fmac_f32_dpp v8, v240, v104 row_newbcast:9 row_mask:0xf bank_mask:0xf
	v_fmac_f32_dpp v9, v240, v105 row_newbcast:9 row_mask:0xf bank_mask:0xf
	v_fmac_f32_dpp v10, v240, v106 row_newbcast:9 row_mask:0xf bank_mask:0xf
	v_fmac_f32_dpp v11, v240, v107 row_newbcast:9 row_mask:0xf bank_mask:0xf
	v_fmac_f32_dpp v12, v240, v108 row_newbcast:9 row_mask:0xf bank_mask:0xf
	v_fmac_f32_dpp v13, v240, v109 row_newbcast:9 row_mask:0xf bank_mask:0xf
	v_fmac_f32_dpp v14, v240, v110 row_newbcast:9 row_mask:0xf bank_mask:0xf
	v_fmac_f32_dpp v15, v240, v111 row_newbcast:9 row_mask:0xf bank_mask:0xf
	global_load_dwordx4 v[104:107], v28, s[2:3] offset:2048 nt
	global_load_dwordx4 v[108:111], v28, s[2:3] offset:2064 nt
	s_waitcnt vmcnt(30)
	v_fmac_f32_dpp v8, v240, v112 row_newbcast:10 row_mask:0xf bank_mask:0xf
	v_fmac_f32_dpp v9, v240, v113 row_newbcast:10 row_mask:0xf bank_mask:0xf
	v_fmac_f32_dpp v10, v240, v114 row_newbcast:10 row_mask:0xf bank_mask:0xf
	v_fmac_f32_dpp v11, v240, v115 row_newbcast:10 row_mask:0xf bank_mask:0xf
	v_fmac_f32_dpp v12, v240, v116 row_newbcast:10 row_mask:0xf bank_mask:0xf
	v_fmac_f32_dpp v13, v240, v117 row_newbcast:10 row_mask:0xf bank_mask:0xf
	v_fmac_f32_dpp v14, v240, v118 row_newbcast:10 row_mask:0xf bank_mask:0xf
	v_fmac_f32_dpp v15, v240, v119 row_newbcast:10 row_mask:0xf bank_mask:0xf
	global_load_dwordx4 v[112:115], v29, s[2:3] nt
	global_load_dwordx4 v[116:119], v29, s[2:3] offset:16 nt
	s_waitcnt vmcnt(30)
	v_fmac_f32_dpp v8, v240, v120 row_newbcast:11 row_mask:0xf bank_mask:0xf
	v_fmac_f32_dpp v9, v240, v121 row_newbcast:11 row_mask:0xf bank_mask:0xf
	v_fmac_f32_dpp v10, v240, v122 row_newbcast:11 row_mask:0xf bank_mask:0xf
	v_fmac_f32_dpp v11, v240, v123 row_newbcast:11 row_mask:0xf bank_mask:0xf
	v_fmac_f32_dpp v12, v240, v124 row_newbcast:11 row_mask:0xf bank_mask:0xf
	v_fmac_f32_dpp v13, v240, v125 row_newbcast:11 row_mask:0xf bank_mask:0xf
	v_fmac_f32_dpp v14, v240, v126 row_newbcast:11 row_mask:0xf bank_mask:0xf
	v_fmac_f32_dpp v15, v240, v127 row_newbcast:11 row_mask:0xf bank_mask:0xf
	global_load_dwordx4 v[120:123], v29, s[2:3] offset:2048 nt
	global_load_dwordx4 v[124:127], v29, s[2:3] offset:2064 nt
	s_waitcnt vmcnt(30)
	v_fmac_f32_dpp v8, v240, v128 row_newbcast:12 row_mask:0xf bank_mask:0xf
	v_fmac_f32_dpp v9, v240, v129 row_newbcast:12 row_mask:0xf bank_mask:0xf
	v_fmac_f32_dpp v10, v240, v130 row_newbcast:12 row_mask:0xf bank_mask:0xf
	v_fmac_f32_dpp v11, v240, v131 row_newbcast:12 row_mask:0xf bank_mask:0xf
	v_fmac_f32_dpp v12, v240, v132 row_newbcast:12 row_mask:0xf bank_mask:0xf
	v_fmac_f32_dpp v13, v240, v133 row_newbcast:12 row_mask:0xf bank_mask:0xf
	v_fmac_f32_dpp v14, v240, v134 row_newbcast:12 row_mask:0xf bank_mask:0xf
	v_fmac_f32_dpp v15, v240, v135 row_newbcast:12 row_mask:0xf bank_mask:0xf
	global_load_dwordx4 v[128:131], v30, s[2:3] nt
	global_load_dwordx4 v[132:135], v30, s[2:3] offset:16 nt
	s_waitcnt vmcnt(30)
	v_fmac_f32_dpp v8, v240, v136 row_newbcast:13 row_mask:0xf bank_mask:0xf
	v_fmac_f32_dpp v9, v240, v137 row_newbcast:13 row_mask:0xf bank_mask:0xf
	v_fmac_f32_dpp v10, v240, v138 row_newbcast:13 row_mask:0xf bank_mask:0xf
	v_fmac_f32_dpp v11, v240, v139 row_newbcast:13 row_mask:0xf bank_mask:0xf
	v_fmac_f32_dpp v12, v240, v140 row_newbcast:13 row_mask:0xf bank_mask:0xf
	v_fmac_f32_dpp v13, v240, v141 row_newbcast:13 row_mask:0xf bank_mask:0xf
	v_fmac_f32_dpp v14, v240, v142 row_newbcast:13 row_mask:0xf bank_mask:0xf
	v_fmac_f32_dpp v15, v240, v143 row_newbcast:13 row_mask:0xf bank_mask:0xf
	global_load_dwordx4 v[136:139], v30, s[2:3] offset:2048 nt
	global_load_dwordx4 v[140:143], v30, s[2:3] offset:2064 nt
	s_waitcnt vmcnt(30)
	v_fmac_f32_dpp v8, v240, v144 row_newbcast:14 row_mask:0xf bank_mask:0xf
	v_fmac_f32_dpp v9, v240, v145 row_newbcast:14 row_mask:0xf bank_mask:0xf
	v_fmac_f32_dpp v10, v240, v146 row_newbcast:14 row_mask:0xf bank_mask:0xf
	v_fmac_f32_dpp v11, v240, v147 row_newbcast:14 row_mask:0xf bank_mask:0xf
	v_fmac_f32_dpp v12, v240, v148 row_newbcast:14 row_mask:0xf bank_mask:0xf
	v_fmac_f32_dpp v13, v240, v149 row_newbcast:14 row_mask:0xf bank_mask:0xf
	v_fmac_f32_dpp v14, v240, v150 row_newbcast:14 row_mask:0xf bank_mask:0xf
	v_fmac_f32_dpp v15, v240, v151 row_newbcast:14 row_mask:0xf bank_mask:0xf
	global_load_dwordx4 v[144:147], v31, s[2:3] nt
	global_load_dwordx4 v[148:151], v31, s[2:3] offset:16 nt
	s_waitcnt vmcnt(30)
	v_fmac_f32_dpp v8, v240, v152 row_newbcast:15 row_mask:0xf bank_mask:0xf
	v_fmac_f32_dpp v9, v240, v153 row_newbcast:15 row_mask:0xf bank_mask:0xf
	v_fmac_f32_dpp v10, v240, v154 row_newbcast:15 row_mask:0xf bank_mask:0xf
	v_fmac_f32_dpp v11, v240, v155 row_newbcast:15 row_mask:0xf bank_mask:0xf
	v_fmac_f32_dpp v12, v240, v156 row_newbcast:15 row_mask:0xf bank_mask:0xf
	v_fmac_f32_dpp v13, v240, v157 row_newbcast:15 row_mask:0xf bank_mask:0xf
	v_fmac_f32_dpp v14, v240, v158 row_newbcast:15 row_mask:0xf bank_mask:0xf
	v_fmac_f32_dpp v15, v240, v159 row_newbcast:15 row_mask:0xf bank_mask:0xf
	global_load_dwordx4 v[152:155], v31, s[2:3] offset:2048 nt
	global_load_dwordx4 v[156:159], v31, s[2:3] offset:2064 nt
	s_waitcnt vmcnt(30)
	v_mul_f32_e32 v160, v32, v0
	v_fmac_f32_e32 v160, v33, v1
	v_fmac_f32_e32 v160, v34, v2
	v_fmac_f32_e32 v160, v35, v3
	v_fmac_f32_e32 v160, v36, v4
	v_fmac_f32_e32 v160, v37, v5
	v_fmac_f32_e32 v160, v38, v6
	v_fmac_f32_e32 v160, v39, v7
	global_load_dwordx4 v[32:35], v24, s[4:5] nt
	global_load_dwordx4 v[36:39], v24, s[4:5] offset:16 nt
	s_waitcnt vmcnt(30)
	v_mul_f32_e32 v161, v40, v0
	v_fmac_f32_e32 v161, v41, v1
	v_fmac_f32_e32 v161, v42, v2
	v_fmac_f32_e32 v161, v43, v3
	v_fmac_f32_e32 v161, v44, v4
	v_fmac_f32_e32 v161, v45, v5
	v_fmac_f32_e32 v161, v46, v6
	v_fmac_f32_e32 v161, v47, v7
	global_load_dwordx4 v[40:43], v24, s[4:5] offset:2048 nt
	global_load_dwordx4 v[44:47], v24, s[4:5] offset:2064 nt
	s_waitcnt vmcnt(30)
	v_mul_f32_e32 v162, v48, v0
	v_fmac_f32_e32 v162, v49, v1
	v_fmac_f32_e32 v162, v50, v2
	v_fmac_f32_e32 v162, v51, v3
	v_fmac_f32_e32 v162, v52, v4
	v_fmac_f32_e32 v162, v53, v5
	v_fmac_f32_e32 v162, v54, v6
	v_fmac_f32_e32 v162, v55, v7
	global_load_dwordx4 v[48:51], v25, s[4:5] nt
	global_load_dwordx4 v[52:55], v25, s[4:5] offset:16 nt
	s_waitcnt vmcnt(30)
	v_mul_f32_e32 v163, v56, v0
	v_fmac_f32_e32 v163, v57, v1
	v_fmac_f32_e32 v163, v58, v2
	v_fmac_f32_e32 v163, v59, v3
	v_fmac_f32_e32 v163, v60, v4
	v_fmac_f32_e32 v163, v61, v5
	v_fmac_f32_e32 v163, v62, v6
	v_fmac_f32_e32 v163, v63, v7
	global_load_dwordx4 v[56:59], v25, s[4:5] offset:2048 nt
	global_load_dwordx4 v[60:63], v25, s[4:5] offset:2064 nt
	s_waitcnt vmcnt(30)
	v_mul_f32_e32 v164, v64, v0
	v_fmac_f32_e32 v164, v65, v1
	v_fmac_f32_e32 v164, v66, v2
	v_fmac_f32_e32 v164, v67, v3
	v_fmac_f32_e32 v164, v68, v4
	v_fmac_f32_e32 v164, v69, v5
	v_fmac_f32_e32 v164, v70, v6
	v_fmac_f32_e32 v164, v71, v7
	global_load_dwordx4 v[64:67], v26, s[4:5] nt
	global_load_dwordx4 v[68:71], v26, s[4:5] offset:16 nt
	s_waitcnt vmcnt(30)
	v_mul_f32_e32 v165, v72, v0
	v_fmac_f32_e32 v165, v73, v1
	v_fmac_f32_e32 v165, v74, v2
	v_fmac_f32_e32 v165, v75, v3
	v_fmac_f32_e32 v165, v76, v4
	v_fmac_f32_e32 v165, v77, v5
	v_fmac_f32_e32 v165, v78, v6
	v_fmac_f32_e32 v165, v79, v7
	global_load_dwordx4 v[72:75], v26, s[4:5] offset:2048 nt
	global_load_dwordx4 v[76:79], v26, s[4:5] offset:2064 nt
	s_waitcnt vmcnt(30)
	v_mul_f32_e32 v166, v80, v0
	v_fmac_f32_e32 v166, v81, v1
	v_fmac_f32_e32 v166, v82, v2
	v_fmac_f32_e32 v166, v83, v3
	v_fmac_f32_e32 v166, v84, v4
	v_fmac_f32_e32 v166, v85, v5
	v_fmac_f32_e32 v166, v86, v6
	v_fmac_f32_e32 v166, v87, v7
	global_load_dwordx4 v[80:83], v27, s[4:5] nt
	global_load_dwordx4 v[84:87], v27, s[4:5] offset:16 nt
	s_waitcnt vmcnt(30)
	v_mul_f32_e32 v167, v88, v0
	v_fmac_f32_e32 v167, v89, v1
	v_fmac_f32_e32 v167, v90, v2
	v_fmac_f32_e32 v167, v91, v3
	v_fmac_f32_e32 v167, v92, v4
	v_fmac_f32_e32 v167, v93, v5
	v_fmac_f32_e32 v167, v94, v6
	v_fmac_f32_e32 v167, v95, v7
	global_load_dwordx4 v[88:91], v27, s[4:5] offset:2048 nt
	global_load_dwordx4 v[92:95], v27, s[4:5] offset:2064 nt
	s_waitcnt vmcnt(30)
	v_mul_f32_e32 v168, v96, v0
	v_fmac_f32_e32 v168, v97, v1
	v_fmac_f32_e32 v168, v98, v2
	v_fmac_f32_e32 v168, v99, v3
	v_fmac_f32_e32 v168, v100, v4
	v_fmac_f32_e32 v168, v101, v5
	v_fmac_f32_e32 v168, v102, v6
	v_fmac_f32_e32 v168, v103, v7
	global_load_dwordx4 v[96:99], v28, s[4:5] nt
	global_load_dwordx4 v[100:103], v28, s[4:5] offset:16 nt
	s_waitcnt vmcnt(30)
	v_mul_f32_e32 v169, v104, v0
	v_fmac_f32_e32 v169, v105, v1
	v_fmac_f32_e32 v169, v106, v2
	v_fmac_f32_e32 v169, v107, v3
	v_fmac_f32_e32 v169, v108, v4
	v_fmac_f32_e32 v169, v109, v5
	v_fmac_f32_e32 v169, v110, v6
	v_fmac_f32_e32 v169, v111, v7
	global_load_dwordx4 v[104:107], v28, s[4:5] offset:2048 nt
	global_load_dwordx4 v[108:111], v28, s[4:5] offset:2064 nt
	s_waitcnt vmcnt(30)
	v_mul_f32_e32 v170, v112, v0
	v_fmac_f32_e32 v170, v113, v1
	v_fmac_f32_e32 v170, v114, v2
	v_fmac_f32_e32 v170, v115, v3
	v_fmac_f32_e32 v170, v116, v4
	v_fmac_f32_e32 v170, v117, v5
	v_fmac_f32_e32 v170, v118, v6
	v_fmac_f32_e32 v170, v119, v7
	global_load_dwordx4 v[112:115], v29, s[4:5] nt
	global_load_dwordx4 v[116:119], v29, s[4:5] offset:16 nt
	s_waitcnt vmcnt(30)
	v_mul_f32_e32 v171, v120, v0
	v_fmac_f32_e32 v171, v121, v1
	v_fmac_f32_e32 v171, v122, v2
	v_fmac_f32_e32 v171, v123, v3
	v_fmac_f32_e32 v171, v124, v4
	v_fmac_f32_e32 v171, v125, v5
	v_fmac_f32_e32 v171, v126, v6
	v_fmac_f32_e32 v171, v127, v7
	global_load_dwordx4 v[120:123], v29, s[4:5] offset:2048 nt
	global_load_dwordx4 v[124:127], v29, s[4:5] offset:2064 nt
	s_waitcnt vmcnt(30)
	v_mul_f32_e32 v172, v128, v0
	v_fmac_f32_e32 v172, v129, v1
	v_fmac_f32_e32 v172, v130, v2
	v_fmac_f32_e32 v172, v131, v3
	v_fmac_f32_e32 v172, v132, v4
	v_fmac_f32_e32 v172, v133, v5
	v_fmac_f32_e32 v172, v134, v6
	v_fmac_f32_e32 v172, v135, v7
	global_load_dwordx4 v[128:131], v30, s[4:5] nt
	global_load_dwordx4 v[132:135], v30, s[4:5] offset:16 nt
	s_waitcnt vmcnt(30)
	v_mul_f32_e32 v173, v136, v0
	v_fmac_f32_e32 v173, v137, v1
	v_fmac_f32_e32 v173, v138, v2
	v_fmac_f32_e32 v173, v139, v3
	v_fmac_f32_e32 v173, v140, v4
	v_fmac_f32_e32 v173, v141, v5
	v_fmac_f32_e32 v173, v142, v6
	v_fmac_f32_e32 v173, v143, v7
	global_load_dwordx4 v[136:139], v30, s[4:5] offset:2048 nt
	global_load_dwordx4 v[140:143], v30, s[4:5] offset:2064 nt
	s_waitcnt vmcnt(30)
	v_mul_f32_e32 v174, v144, v0
	v_fmac_f32_e32 v174, v145, v1
	v_fmac_f32_e32 v174, v146, v2
	v_fmac_f32_e32 v174, v147, v3
	v_fmac_f32_e32 v174, v148, v4
	v_fmac_f32_e32 v174, v149, v5
	v_fmac_f32_e32 v174, v150, v6
	v_fmac_f32_e32 v174, v151, v7
	global_load_dwordx4 v[144:147], v31, s[4:5] nt
	global_load_dwordx4 v[148:151], v31, s[4:5] offset:16 nt
	s_waitcnt vmcnt(30)
	v_mul_f32_e32 v175, v152, v0
	v_fmac_f32_e32 v175, v153, v1
	v_fmac_f32_e32 v175, v154, v2
	v_fmac_f32_e32 v175, v155, v3
	v_fmac_f32_e32 v175, v156, v4
	v_fmac_f32_e32 v175, v157, v5
	v_fmac_f32_e32 v175, v158, v6
	v_fmac_f32_e32 v175, v159, v7
	global_load_dwordx4 v[152:155], v31, s[4:5] offset:2048 nt
	global_load_dwordx4 v[156:159], v31, s[4:5] offset:2064 nt
	v_add_f32_dpp v160, v160, v160 row_ror:8 row_mask:0xf bank_mask:0x3
	v_add_f32_dpp v160, v168, v168 row_ror:8 row_mask:0xf bank_mask:0xc
	v_add_f32_dpp v161, v161, v161 row_ror:8 row_mask:0xf bank_mask:0x3
	v_add_f32_dpp v161, v169, v169 row_ror:8 row_mask:0xf bank_mask:0xc
	v_add_f32_dpp v162, v162, v162 row_ror:8 row_mask:0xf bank_mask:0x3
	v_add_f32_dpp v162, v170, v170 row_ror:8 row_mask:0xf bank_mask:0xc
	v_add_f32_dpp v163, v163, v163 row_ror:8 row_mask:0xf bank_mask:0x3
	v_add_f32_dpp v163, v171, v171 row_ror:8 row_mask:0xf bank_mask:0xc
	v_add_f32_dpp v164, v164, v164 row_ror:8 row_mask:0xf bank_mask:0x3
	v_add_f32_dpp v164, v172, v172 row_ror:8 row_mask:0xf bank_mask:0xc
	v_add_f32_dpp v165, v165, v165 row_ror:8 row_mask:0xf bank_mask:0x3
	v_add_f32_dpp v165, v173, v173 row_ror:8 row_mask:0xf bank_mask:0xc
	v_add_f32_dpp v166, v166, v166 row_ror:8 row_mask:0xf bank_mask:0x3
	v_add_f32_dpp v166, v174, v174 row_ror:8 row_mask:0xf bank_mask:0xc
	v_add_f32_dpp v167, v167, v167 row_ror:8 row_mask:0xf bank_mask:0x3
	v_add_f32_dpp v167, v175, v175 row_ror:8 row_mask:0xf bank_mask:0xc
	v_add_f32_dpp v160, v160, v160 row_shl:4 row_mask:0xf bank_mask:0x5
	v_add_f32_dpp v160, v164, v164 row_shr:4 row_mask:0xf bank_mask:0xa
	v_add_f32_dpp v161, v161, v161 row_shl:4 row_mask:0xf bank_mask:0x5
	v_add_f32_dpp v161, v165, v165 row_shr:4 row_mask:0xf bank_mask:0xa
	v_add_f32_dpp v162, v162, v162 row_shl:4 row_mask:0xf bank_mask:0x5
	v_add_f32_dpp v162, v166, v166 row_shr:4 row_mask:0xf bank_mask:0xa
	v_add_f32_dpp v163, v163, v163 row_shl:4 row_mask:0xf bank_mask:0x5
	v_add_f32_dpp v163, v167, v167 row_shr:4 row_mask:0xf bank_mask:0xa
	v_and_b32_e32 v176, 2, v18
	v_cmp_ne_u32_e32 vcc, 0, v176
	v_add_f32_dpp v230, v160, v160 quad_perm:[2,3,0,1] row_mask:0xf bank_mask:0xf
	v_add_f32_dpp v231, v162, v162 quad_perm:[2,3,0,1] row_mask:0xf bank_mask:0xf
	v_add_f32_dpp v232, v161, v161 quad_perm:[2,3,0,1] row_mask:0xf bank_mask:0xf
	v_add_f32_dpp v233, v163, v163 quad_perm:[2,3,0,1] row_mask:0xf bank_mask:0xf
	v_cndmask_b32_e32 v230, v230, v231, vcc
	v_cndmask_b32_e32 v232, v232, v233, vcc
	v_and_b32_e32 v176, 1, v18
	v_cmp_ne_u32_e32 vcc, 0, v176
	v_add_f32_dpp v231, v230, v230 quad_perm:[1,0,3,2] row_mask:0xf bank_mask:0xf
	v_add_f32_dpp v233, v232, v232 quad_perm:[1,0,3,2] row_mask:0xf bank_mask:0xf
	s_nop 1
	v_cndmask_b32_e32 v241, v231, v233, vcc
	s_nop 1
	v_max_f32_dpp v242, v241, v241 row_ror:8 row_mask:0xf bank_mask:0xf
	s_nop 1
	v_max_f32_dpp v242, v242, v242 row_ror:4 row_mask:0xf bank_mask:0xf
	s_nop 1
	v_max_f32_dpp v242, v242, v242 row_ror:2 row_mask:0xf bank_mask:0xf
	s_nop 1
	v_max_f32_dpp v242, v242, v242 row_ror:1 row_mask:0xf bank_mask:0xf
	ds_bpermute_b32 v234, v238, v242
	s_waitcnt lgkmcnt(0)
	v_max_f32_e32 v242, v242, v234
	ds_bpermute_b32 v234, v239, v242
	s_waitcnt lgkmcnt(0)
	v_max_f32_e32 v242, v242, v234
	v_max_f32_e32 v242, v16, v242
	v_sub_f32_e32 v243, v16, v242
	v_sub_f32_e32 v240, v241, v242
	v_mul_f32_e32 v243, 0x3fb8aa3b, v243
	v_mul_f32_e32 v240, 0x3fb8aa3b, v240
	v_exp_f32_e32 v243, v243
	v_exp_f32_e32 v240, v240
	v_mov_b32_e32 v16, v242
	s_nop 0
	s_nop 1
	v_add_f32_dpp v235, v240, v240 row_ror:8 row_mask:0xf bank_mask:0xf
	s_nop 1
	v_add_f32_dpp v235, v235, v235 row_ror:4 row_mask:0xf bank_mask:0xf
	s_nop 1
	v_add_f32_dpp v235, v235, v235 row_ror:2 row_mask:0xf bank_mask:0xf
	s_nop 1
	v_add_f32_dpp v235, v235, v235 row_ror:1 row_mask:0xf bank_mask:0xf
	ds_bpermute_b32 v234, v238, v235
	s_waitcnt lgkmcnt(0)
	v_add_f32_e32 v235, v235, v234
	ds_bpermute_b32 v234, v239, v235
	s_waitcnt lgkmcnt(0)
	v_add_f32_e32 v235, v235, v234
	v_fma_f32 v17, v17, v243, v235
	v_mul_f32_e32 v8, v8, v243
	v_mul_f32_e32 v9, v9, v243
	v_mul_f32_e32 v10, v10, v243
	v_mul_f32_e32 v11, v11, v243
	v_mul_f32_e32 v12, v12, v243
	v_mul_f32_e32 v13, v13, v243
	v_mul_f32_e32 v14, v14, v243
	v_mul_f32_e32 v15, v15, v243
	s_waitcnt vmcnt(30)
	v_fmac_f32_dpp v8, v240, v32 row_newbcast:0 row_mask:0xf bank_mask:0xf
	v_fmac_f32_dpp v9, v240, v33 row_newbcast:0 row_mask:0xf bank_mask:0xf
	v_fmac_f32_dpp v10, v240, v34 row_newbcast:0 row_mask:0xf bank_mask:0xf
	v_fmac_f32_dpp v11, v240, v35 row_newbcast:0 row_mask:0xf bank_mask:0xf
	v_fmac_f32_dpp v12, v240, v36 row_newbcast:0 row_mask:0xf bank_mask:0xf
	v_fmac_f32_dpp v13, v240, v37 row_newbcast:0 row_mask:0xf bank_mask:0xf
	v_fmac_f32_dpp v14, v240, v38 row_newbcast:0 row_mask:0xf bank_mask:0xf
	v_fmac_f32_dpp v15, v240, v39 row_newbcast:0 row_mask:0xf bank_mask:0xf
	s_waitcnt vmcnt(28)
	v_fmac_f32_dpp v8, v240, v40 row_newbcast:1 row_mask:0xf bank_mask:0xf
	v_fmac_f32_dpp v9, v240, v41 row_newbcast:1 row_mask:0xf bank_mask:0xf
	v_fmac_f32_dpp v10, v240, v42 row_newbcast:1 row_mask:0xf bank_mask:0xf
	v_fmac_f32_dpp v11, v240, v43 row_newbcast:1 row_mask:0xf bank_mask:0xf
	v_fmac_f32_dpp v12, v240, v44 row_newbcast:1 row_mask:0xf bank_mask:0xf
	v_fmac_f32_dpp v13, v240, v45 row_newbcast:1 row_mask:0xf bank_mask:0xf
	v_fmac_f32_dpp v14, v240, v46 row_newbcast:1 row_mask:0xf bank_mask:0xf
	v_fmac_f32_dpp v15, v240, v47 row_newbcast:1 row_mask:0xf bank_mask:0xf
	s_waitcnt vmcnt(26)
	v_fmac_f32_dpp v8, v240, v48 row_newbcast:2 row_mask:0xf bank_mask:0xf
	v_fmac_f32_dpp v9, v240, v49 row_newbcast:2 row_mask:0xf bank_mask:0xf
	v_fmac_f32_dpp v10, v240, v50 row_newbcast:2 row_mask:0xf bank_mask:0xf
	v_fmac_f32_dpp v11, v240, v51 row_newbcast:2 row_mask:0xf bank_mask:0xf
	v_fmac_f32_dpp v12, v240, v52 row_newbcast:2 row_mask:0xf bank_mask:0xf
	v_fmac_f32_dpp v13, v240, v53 row_newbcast:2 row_mask:0xf bank_mask:0xf
	v_fmac_f32_dpp v14, v240, v54 row_newbcast:2 row_mask:0xf bank_mask:0xf
	v_fmac_f32_dpp v15, v240, v55 row_newbcast:2 row_mask:0xf bank_mask:0xf
	s_waitcnt vmcnt(24)
	v_fmac_f32_dpp v8, v240, v56 row_newbcast:3 row_mask:0xf bank_mask:0xf
	v_fmac_f32_dpp v9, v240, v57 row_newbcast:3 row_mask:0xf bank_mask:0xf
	v_fmac_f32_dpp v10, v240, v58 row_newbcast:3 row_mask:0xf bank_mask:0xf
	v_fmac_f32_dpp v11, v240, v59 row_newbcast:3 row_mask:0xf bank_mask:0xf
	v_fmac_f32_dpp v12, v240, v60 row_newbcast:3 row_mask:0xf bank_mask:0xf
	v_fmac_f32_dpp v13, v240, v61 row_newbcast:3 row_mask:0xf bank_mask:0xf
	v_fmac_f32_dpp v14, v240, v62 row_newbcast:3 row_mask:0xf bank_mask:0xf
	v_fmac_f32_dpp v15, v240, v63 row_newbcast:3 row_mask:0xf bank_mask:0xf
	s_waitcnt vmcnt(22)
	v_fmac_f32_dpp v8, v240, v64 row_newbcast:4 row_mask:0xf bank_mask:0xf
	v_fmac_f32_dpp v9, v240, v65 row_newbcast:4 row_mask:0xf bank_mask:0xf
	v_fmac_f32_dpp v10, v240, v66 row_newbcast:4 row_mask:0xf bank_mask:0xf
	v_fmac_f32_dpp v11, v240, v67 row_newbcast:4 row_mask:0xf bank_mask:0xf
	v_fmac_f32_dpp v12, v240, v68 row_newbcast:4 row_mask:0xf bank_mask:0xf
	v_fmac_f32_dpp v13, v240, v69 row_newbcast:4 row_mask:0xf bank_mask:0xf
	v_fmac_f32_dpp v14, v240, v70 row_newbcast:4 row_mask:0xf bank_mask:0xf
	v_fmac_f32_dpp v15, v240, v71 row_newbcast:4 row_mask:0xf bank_mask:0xf
	s_waitcnt vmcnt(20)
	v_fmac_f32_dpp v8, v240, v72 row_newbcast:5 row_mask:0xf bank_mask:0xf
	v_fmac_f32_dpp v9, v240, v73 row_newbcast:5 row_mask:0xf bank_mask:0xf
	v_fmac_f32_dpp v10, v240, v74 row_newbcast:5 row_mask:0xf bank_mask:0xf
	v_fmac_f32_dpp v11, v240, v75 row_newbcast:5 row_mask:0xf bank_mask:0xf
	v_fmac_f32_dpp v12, v240, v76 row_newbcast:5 row_mask:0xf bank_mask:0xf
	v_fmac_f32_dpp v13, v240, v77 row_newbcast:5 row_mask:0xf bank_mask:0xf
	v_fmac_f32_dpp v14, v240, v78 row_newbcast:5 row_mask:0xf bank_mask:0xf
	v_fmac_f32_dpp v15, v240, v79 row_newbcast:5 row_mask:0xf bank_mask:0xf
	s_waitcnt vmcnt(18)
	v_fmac_f32_dpp v8, v240, v80 row_newbcast:6 row_mask:0xf bank_mask:0xf
	v_fmac_f32_dpp v9, v240, v81 row_newbcast:6 row_mask:0xf bank_mask:0xf
	v_fmac_f32_dpp v10, v240, v82 row_newbcast:6 row_mask:0xf bank_mask:0xf
	v_fmac_f32_dpp v11, v240, v83 row_newbcast:6 row_mask:0xf bank_mask:0xf
	v_fmac_f32_dpp v12, v240, v84 row_newbcast:6 row_mask:0xf bank_mask:0xf
	v_fmac_f32_dpp v13, v240, v85 row_newbcast:6 row_mask:0xf bank_mask:0xf
	v_fmac_f32_dpp v14, v240, v86 row_newbcast:6 row_mask:0xf bank_mask:0xf
	v_fmac_f32_dpp v15, v240, v87 row_newbcast:6 row_mask:0xf bank_mask:0xf
	s_waitcnt vmcnt(16)
	v_fmac_f32_dpp v8, v240, v88 row_newbcast:7 row_mask:0xf bank_mask:0xf
	v_fmac_f32_dpp v9, v240, v89 row_newbcast:7 row_mask:0xf bank_mask:0xf
	v_fmac_f32_dpp v10, v240, v90 row_newbcast:7 row_mask:0xf bank_mask:0xf
	v_fmac_f32_dpp v11, v240, v91 row_newbcast:7 row_mask:0xf bank_mask:0xf
	v_fmac_f32_dpp v12, v240, v92 row_newbcast:7 row_mask:0xf bank_mask:0xf
	v_fmac_f32_dpp v13, v240, v93 row_newbcast:7 row_mask:0xf bank_mask:0xf
	v_fmac_f32_dpp v14, v240, v94 row_newbcast:7 row_mask:0xf bank_mask:0xf
	v_fmac_f32_dpp v15, v240, v95 row_newbcast:7 row_mask:0xf bank_mask:0xf
	s_waitcnt vmcnt(14)
	v_fmac_f32_dpp v8, v240, v96 row_newbcast:8 row_mask:0xf bank_mask:0xf
	v_fmac_f32_dpp v9, v240, v97 row_newbcast:8 row_mask:0xf bank_mask:0xf
	v_fmac_f32_dpp v10, v240, v98 row_newbcast:8 row_mask:0xf bank_mask:0xf
	v_fmac_f32_dpp v11, v240, v99 row_newbcast:8 row_mask:0xf bank_mask:0xf
	v_fmac_f32_dpp v12, v240, v100 row_newbcast:8 row_mask:0xf bank_mask:0xf
	v_fmac_f32_dpp v13, v240, v101 row_newbcast:8 row_mask:0xf bank_mask:0xf
	v_fmac_f32_dpp v14, v240, v102 row_newbcast:8 row_mask:0xf bank_mask:0xf
	v_fmac_f32_dpp v15, v240, v103 row_newbcast:8 row_mask:0xf bank_mask:0xf
	s_waitcnt vmcnt(12)
	v_fmac_f32_dpp v8, v240, v104 row_newbcast:9 row_mask:0xf bank_mask:0xf
	v_fmac_f32_dpp v9, v240, v105 row_newbcast:9 row_mask:0xf bank_mask:0xf
	v_fmac_f32_dpp v10, v240, v106 row_newbcast:9 row_mask:0xf bank_mask:0xf
	v_fmac_f32_dpp v11, v240, v107 row_newbcast:9 row_mask:0xf bank_mask:0xf
	v_fmac_f32_dpp v12, v240, v108 row_newbcast:9 row_mask:0xf bank_mask:0xf
	v_fmac_f32_dpp v13, v240, v109 row_newbcast:9 row_mask:0xf bank_mask:0xf
	v_fmac_f32_dpp v14, v240, v110 row_newbcast:9 row_mask:0xf bank_mask:0xf
	v_fmac_f32_dpp v15, v240, v111 row_newbcast:9 row_mask:0xf bank_mask:0xf
	s_waitcnt vmcnt(10)
	v_fmac_f32_dpp v8, v240, v112 row_newbcast:10 row_mask:0xf bank_mask:0xf
	v_fmac_f32_dpp v9, v240, v113 row_newbcast:10 row_mask:0xf bank_mask:0xf
	v_fmac_f32_dpp v10, v240, v114 row_newbcast:10 row_mask:0xf bank_mask:0xf
	v_fmac_f32_dpp v11, v240, v115 row_newbcast:10 row_mask:0xf bank_mask:0xf
	v_fmac_f32_dpp v12, v240, v116 row_newbcast:10 row_mask:0xf bank_mask:0xf
	v_fmac_f32_dpp v13, v240, v117 row_newbcast:10 row_mask:0xf bank_mask:0xf
	v_fmac_f32_dpp v14, v240, v118 row_newbcast:10 row_mask:0xf bank_mask:0xf
	v_fmac_f32_dpp v15, v240, v119 row_newbcast:10 row_mask:0xf bank_mask:0xf
	s_waitcnt vmcnt(8)
	v_fmac_f32_dpp v8, v240, v120 row_newbcast:11 row_mask:0xf bank_mask:0xf
	v_fmac_f32_dpp v9, v240, v121 row_newbcast:11 row_mask:0xf bank_mask:0xf
	v_fmac_f32_dpp v10, v240, v122 row_newbcast:11 row_mask:0xf bank_mask:0xf
	v_fmac_f32_dpp v11, v240, v123 row_newbcast:11 row_mask:0xf bank_mask:0xf
	v_fmac_f32_dpp v12, v240, v124 row_newbcast:11 row_mask:0xf bank_mask:0xf
	v_fmac_f32_dpp v13, v240, v125 row_newbcast:11 row_mask:0xf bank_mask:0xf
	v_fmac_f32_dpp v14, v240, v126 row_newbcast:11 row_mask:0xf bank_mask:0xf
	v_fmac_f32_dpp v15, v240, v127 row_newbcast:11 row_mask:0xf bank_mask:0xf
	s_waitcnt vmcnt(6)
	v_fmac_f32_dpp v8, v240, v128 row_newbcast:12 row_mask:0xf bank_mask:0xf
	v_fmac_f32_dpp v9, v240, v129 row_newbcast:12 row_mask:0xf bank_mask:0xf
	v_fmac_f32_dpp v10, v240, v130 row_newbcast:12 row_mask:0xf bank_mask:0xf
	v_fmac_f32_dpp v11, v240, v131 row_newbcast:12 row_mask:0xf bank_mask:0xf
	v_fmac_f32_dpp v12, v240, v132 row_newbcast:12 row_mask:0xf bank_mask:0xf
	v_fmac_f32_dpp v13, v240, v133 row_newbcast:12 row_mask:0xf bank_mask:0xf
	v_fmac_f32_dpp v14, v240, v134 row_newbcast:12 row_mask:0xf bank_mask:0xf
	v_fmac_f32_dpp v15, v240, v135 row_newbcast:12 row_mask:0xf bank_mask:0xf
	s_waitcnt vmcnt(4)
	v_fmac_f32_dpp v8, v240, v136 row_newbcast:13 row_mask:0xf bank_mask:0xf
	v_fmac_f32_dpp v9, v240, v137 row_newbcast:13 row_mask:0xf bank_mask:0xf
	v_fmac_f32_dpp v10, v240, v138 row_newbcast:13 row_mask:0xf bank_mask:0xf
	v_fmac_f32_dpp v11, v240, v139 row_newbcast:13 row_mask:0xf bank_mask:0xf
	v_fmac_f32_dpp v12, v240, v140 row_newbcast:13 row_mask:0xf bank_mask:0xf
	v_fmac_f32_dpp v13, v240, v141 row_newbcast:13 row_mask:0xf bank_mask:0xf
	v_fmac_f32_dpp v14, v240, v142 row_newbcast:13 row_mask:0xf bank_mask:0xf
	v_fmac_f32_dpp v15, v240, v143 row_newbcast:13 row_mask:0xf bank_mask:0xf
	s_waitcnt vmcnt(2)
	v_fmac_f32_dpp v8, v240, v144 row_newbcast:14 row_mask:0xf bank_mask:0xf
	v_fmac_f32_dpp v9, v240, v145 row_newbcast:14 row_mask:0xf bank_mask:0xf
	v_fmac_f32_dpp v10, v240, v146 row_newbcast:14 row_mask:0xf bank_mask:0xf
	v_fmac_f32_dpp v11, v240, v147 row_newbcast:14 row_mask:0xf bank_mask:0xf
	v_fmac_f32_dpp v12, v240, v148 row_newbcast:14 row_mask:0xf bank_mask:0xf
	v_fmac_f32_dpp v13, v240, v149 row_newbcast:14 row_mask:0xf bank_mask:0xf
	v_fmac_f32_dpp v14, v240, v150 row_newbcast:14 row_mask:0xf bank_mask:0xf
	v_fmac_f32_dpp v15, v240, v151 row_newbcast:14 row_mask:0xf bank_mask:0xf
	s_waitcnt vmcnt(0)
	v_fmac_f32_dpp v8, v240, v152 row_newbcast:15 row_mask:0xf bank_mask:0xf
	v_fmac_f32_dpp v9, v240, v153 row_newbcast:15 row_mask:0xf bank_mask:0xf
	v_fmac_f32_dpp v10, v240, v154 row_newbcast:15 row_mask:0xf bank_mask:0xf
	v_fmac_f32_dpp v11, v240, v155 row_newbcast:15 row_mask:0xf bank_mask:0xf
	v_fmac_f32_dpp v12, v240, v156 row_newbcast:15 row_mask:0xf bank_mask:0xf
	v_fmac_f32_dpp v13, v240, v157 row_newbcast:15 row_mask:0xf bank_mask:0xf
	v_fmac_f32_dpp v14, v240, v158 row_newbcast:15 row_mask:0xf bank_mask:0xf
	v_fmac_f32_dpp v15, v240, v159 row_newbcast:15 row_mask:0xf bank_mask:0xf
	ds_bpermute_b32 v160, v238, v8
	ds_bpermute_b32 v161, v238, v9
	ds_bpermute_b32 v162, v238, v10
	ds_bpermute_b32 v163, v238, v11
	ds_bpermute_b32 v164, v238, v12
	ds_bpermute_b32 v165, v238, v13
	ds_bpermute_b32 v166, v238, v14
	ds_bpermute_b32 v167, v238, v15
	s_waitcnt lgkmcnt(0)
	v_add_f32_e32 v8, v8, v160
	v_add_f32_e32 v9, v9, v161
	v_add_f32_e32 v10, v10, v162
	v_add_f32_e32 v11, v11, v163
	v_add_f32_e32 v12, v12, v164
	v_add_f32_e32 v13, v13, v165
	v_add_f32_e32 v14, v14, v166
	v_add_f32_e32 v15, v15, v167
	ds_bpermute_b32 v160, v239, v8
	ds_bpermute_b32 v161, v239, v9
	ds_bpermute_b32 v162, v239, v10
	ds_bpermute_b32 v163, v239, v11
	ds_bpermute_b32 v164, v239, v12
	ds_bpermute_b32 v165, v239, v13
	ds_bpermute_b32 v166, v239, v14
	ds_bpermute_b32 v167, v239, v15
	s_waitcnt lgkmcnt(0)
	v_add_f32_e32 v8, v8, v160
	v_add_f32_e32 v9, v9, v161
	v_add_f32_e32 v10, v10, v162
	v_add_f32_e32 v11, v11, v163
	v_add_f32_e32 v12, v12, v164
	v_add_f32_e32 v13, v13, v165
	v_add_f32_e32 v14, v14, v166
	v_add_f32_e32 v15, v15, v167
	v_lshl_or_b32 v176, v20, 4, v18
	v_mul_u32_u24_e32 v176, 48, v176
	v_cmp_gt_u32_e32 vcc, 16, v18
	v_cmp_eq_u32_e64 s[6:7], 1, v21
	s_and_b64 s[6:7], s[6:7], vcc
	s_and_saveexec_b64 s[6:7], s[6:7]
	v_mov_b32_e32 v160, v16
	v_mov_b32_e32 v161, v17
	v_mov_b32_e32 v162, v8
	v_mov_b32_e32 v163, v9
	ds_write_b128 v176, v[160:163] offset:4096
	ds_write_b128 v176, v[10:13] offset:4112
	ds_write_b64 v176, v[14:15] offset:4128
	s_or_b64 exec, exec, s[6:7]
	s_waitcnt lgkmcnt(0)
	s_barrier
	v_cmp_gt_u32_e32 vcc, 16, v18
	v_cmp_eq_u32_e64 s[6:7], 0, v21
	s_and_b64 s[6:7], s[6:7], vcc
	s_and_saveexec_b64 s[6:7], s[6:7]
	s_cbranch_execz .Lsm0_mdone1
	global_load_dwordx4 v[172:175], v[244:245], off
	ds_read_b128 v[160:163], v176 offset:4096
	ds_read_b128 v[164:167], v176 offset:4112
	ds_read_b64 v[168:169], v176 offset:4128
	s_waitcnt lgkmcnt(0)
	v_max_f32_e32 v230, v16, v160
	v_sub_f32_e32 v231, v16, v230
	v_sub_f32_e32 v232, v160, v230
	v_mul_f32_e32 v231, 0x3fb8aa3b, v231
	v_mul_f32_e32 v232, 0x3fb8aa3b, v232
	v_exp_f32_e32 v231, v231
	v_exp_f32_e32 v232, v232
	s_nop 0
	v_mul_f32_e32 v233, v232, v161
	v_fmac_f32_e32 v233, v231, v17
	v_div_scale_f32 v234, s[8:9], v233, v233, 1.0
	v_rcp_f32_e32 v235, v234
	s_nop 0
	v_fma_f32 v236, -v234, v235, 1.0
	v_fmac_f32_e32 v235, v236, v235
	v_div_scale_f32 v236, vcc, 1.0, v233, 1.0
	v_mul_f32_e32 v237, v236, v235
	v_fma_f32 v176, -v234, v237, v236
	v_fmac_f32_e32 v237, v176, v235
	v_fma_f32 v234, -v234, v237, v236
	s_nop 0
	v_div_fmas_f32 v234, v234, v235, v237
	v_div_fixup_f32 v233, v234, v233, 1.0
	v_mul_f32_e32 v162, v232, v162
	v_fmac_f32_e32 v162, v231, v8
	v_mul_f32_e32 v162, v162, v233
	v_mul_f32_e32 v163, v232, v163
	v_fmac_f32_e32 v163, v231, v9
	v_mul_f32_e32 v163, v163, v233
	v_mul_f32_e32 v164, v232, v164
	v_fmac_f32_e32 v164, v231, v10
	v_mul_f32_e32 v164, v164, v233
	v_mul_f32_e32 v165, v232, v165
	v_fmac_f32_e32 v165, v231, v11
	v_mul_f32_e32 v165, v165, v233
	v_mul_f32_e32 v166, v232, v166
	v_fmac_f32_e32 v166, v231, v12
	v_mul_f32_e32 v166, v166, v233
	v_mul_f32_e32 v167, v232, v167
	v_fmac_f32_e32 v167, v231, v13
	v_mul_f32_e32 v167, v167, v233
	v_mul_f32_e32 v168, v232, v168
	v_fmac_f32_e32 v168, v231, v14
	v_mul_f32_e32 v168, v168, v233
	v_mul_f32_e32 v169, v232, v169
	v_fmac_f32_e32 v169, v231, v15
	v_mul_f32_e32 v169, v169, v233
	s_waitcnt vmcnt(0)
	v_lshlrev_b32_e32 v230, 16, v172
	v_and_b32_e32 v231, 0xffff0000, v172
	v_mul_f32_e32 v236, 0xbfb8aa3b, v230
	v_mul_f32_e32 v237, 0xbfb8aa3b, v231
	v_exp_f32_e32 v236, v236
	v_exp_f32_e32 v237, v237
	s_nop 0
	v_add_f32_e32 v236, 1.0, v236
	v_add_f32_e32 v237, 1.0, v237
	v_rcp_f32_e32 v236, v236
	v_rcp_f32_e32 v237, v237
	s_nop 0
	v_mul_f32_e32 v230, v230, v236
	v_mul_f32_e32 v231, v231, v237
	v_mul_f32_e32 v162, v162, v230
	v_mul_f32_e32 v163, v163, v231
	v_cvt_pk_bf16_f32 v172, v162, v163
	v_lshlrev_b32_e32 v230, 16, v173
	v_and_b32_e32 v231, 0xffff0000, v173
	v_mul_f32_e32 v236, 0xbfb8aa3b, v230
	v_mul_f32_e32 v237, 0xbfb8aa3b, v231
	v_exp_f32_e32 v236, v236
	v_exp_f32_e32 v237, v237
	s_nop 0
	v_add_f32_e32 v236, 1.0, v236
	v_add_f32_e32 v237, 1.0, v237
	v_rcp_f32_e32 v236, v236
	v_rcp_f32_e32 v237, v237
	s_nop 0
	v_mul_f32_e32 v230, v230, v236
	v_mul_f32_e32 v231, v231, v237
	v_mul_f32_e32 v164, v164, v230
	v_mul_f32_e32 v165, v165, v231
	v_cvt_pk_bf16_f32 v173, v164, v165
	v_lshlrev_b32_e32 v230, 16, v174
	v_and_b32_e32 v231, 0xffff0000, v174
	v_mul_f32_e32 v236, 0xbfb8aa3b, v230
	v_mul_f32_e32 v237, 0xbfb8aa3b, v231
	v_exp_f32_e32 v236, v236
	v_exp_f32_e32 v237, v237
	s_nop 0
	v_add_f32_e32 v236, 1.0, v236
	v_add_f32_e32 v237, 1.0, v237
	v_rcp_f32_e32 v236, v236
	v_rcp_f32_e32 v237, v237
	s_nop 0
	v_mul_f32_e32 v230, v230, v236
	v_mul_f32_e32 v231, v231, v237
	v_mul_f32_e32 v166, v166, v230
	v_mul_f32_e32 v167, v167, v231
	v_cvt_pk_bf16_f32 v174, v166, v167
	v_lshlrev_b32_e32 v230, 16, v175
	v_and_b32_e32 v231, 0xffff0000, v175
	v_mul_f32_e32 v236, 0xbfb8aa3b, v230
	v_mul_f32_e32 v237, 0xbfb8aa3b, v231
	v_exp_f32_e32 v236, v236
	v_exp_f32_e32 v237, v237
	s_nop 0
	v_add_f32_e32 v236, 1.0, v236
	v_add_f32_e32 v237, 1.0, v237
	v_rcp_f32_e32 v236, v236
	v_rcp_f32_e32 v237, v237
	s_nop 0
	v_mul_f32_e32 v230, v230, v236
	v_mul_f32_e32 v231, v231, v237
	v_mul_f32_e32 v168, v168, v230
	v_mul_f32_e32 v169, v169, v231
	v_cvt_pk_bf16_f32 v175, v168, v169
	global_store_dwordx4 v[246:247], v[172:175], off

.Lsd_n1:
	global_load_dwordx4 v[32:35], v24, s[2:3] nt
	global_load_dwordx4 v[36:39], v24, s[2:3] offset:16 nt

.Lsd_n3:
	global_load_dwordx4 v[40:43], v25, s[2:3] nt
	global_load_dwordx4 v[44:47], v25, s[2:3] offset:16 nt

.Lsd_n5:
	global_load_dwordx4 v[48:51], v26, s[2:3] nt
	global_load_dwordx4 v[52:55], v26, s[2:3] offset:16 nt
.Lsd_d6:
	global_load_dwordx4 v[56:59], v27, s[2:3] nt
	global_load_dwordx4 v[60:63], v27, s[2:3] offset:16 nt
	global_load_dwordx4 v[64:67], v28, s[2:3] nt
	global_load_dwordx4 v[68:71], v28, s[2:3] offset:16 nt
	global_load_dwordx4 v[72:75], v29, s[2:3] nt
	global_load_dwordx4 v[76:79], v29, s[2:3] offset:16 nt
	global_load_dwordx4 v[80:83], v30, s[2:3] nt
	global_load_dwordx4 v[84:87], v30, s[2:3] offset:16 nt
	global_load_dwordx4 v[88:91], v31, s[2:3] nt
	global_load_dwordx4 v[92:95], v31, s[2:3] offset:16 nt
	global_load_dwordx4 v[96:99], v244, s[2:3] nt
	global_load_dwordx4 v[100:103], v244, s[2:3] offset:16 nt
	global_load_dwordx4 v[104:107], v245, s[2:3] nt
	global_load_dwordx4 v[108:111], v245, s[2:3] offset:16 nt
	global_load_dwordx4 v[112:115], v246, s[2:3] nt
	global_load_dwordx4 v[116:119], v246, s[2:3] offset:16 nt
	global_load_dwordx4 v[120:123], v247, s[2:3] nt
	global_load_dwordx4 v[124:127], v247, s[2:3] offset:16 nt
	global_load_dwordx4 v[128:131], v248, s[2:3] nt
	global_load_dwordx4 v[132:135], v248, s[2:3] offset:16 nt
	global_load_dwordx4 v[136:139], v249, s[2:3] nt
	global_load_dwordx4 v[140:143], v249, s[2:3] offset:16 nt
	global_load_dwordx4 v[144:147], v250, s[2:3] nt
	global_load_dwordx4 v[148:151], v250, s[2:3] offset:16 nt
	global_load_dwordx4 v[152:155], v251, s[2:3] nt
	global_load_dwordx4 v[156:159], v251, s[2:3] offset:16 nt
	s_waitcnt vmcnt(32)
	v_and_b32_e32 v176, 2, v22
	v_cmp_ne_u32_e32 vcc, 0, v176
	v_cmp_gt_u32_e64 s[30:31], 4, v22
	v_lshlrev_b32_e32 v236, 16, v160
	v_and_b32_e32 v237, 0xffff0000, v160
	v_cndmask_b32_e32 v236, v236, v237, vcc
	v_lshlrev_b32_e32 v237, 16, v160
	v_cndmask_b32_e64 v0, v237, v236, s[30:31]
	v_lshlrev_b32_e32 v236, 16, v161
	v_and_b32_e32 v237, 0xffff0000, v161
	v_cndmask_b32_e32 v236, v236, v237, vcc
	v_and_b32_e32 v237, 0xffff0000, v160
	v_cndmask_b32_e64 v1, v237, v236, s[30:31]
	v_lshlrev_b32_e32 v236, 16, v162
	v_and_b32_e32 v237, 0xffff0000, v162
	v_cndmask_b32_e32 v236, v236, v237, vcc
	v_lshlrev_b32_e32 v237, 16, v161
	v_cndmask_b32_e64 v2, v237, v236, s[30:31]
	v_lshlrev_b32_e32 v236, 16, v163
	v_and_b32_e32 v237, 0xffff0000, v163
	v_cndmask_b32_e32 v236, v236, v237, vcc
	v_and_b32_e32 v237, 0xffff0000, v161
	v_cndmask_b32_e64 v3, v237, v236, s[30:31]
	v_lshlrev_b32_e32 v236, 16, v164
	v_and_b32_e32 v237, 0xffff0000, v164
	v_cndmask_b32_e32 v236, v236, v237, vcc
	v_lshlrev_b32_e32 v237, 16, v162
	v_cndmask_b32_e64 v4, v237, v236, s[30:31]
	v_lshlrev_b32_e32 v236, 16, v165
	v_and_b32_e32 v237, 0xffff0000, v165
	v_cndmask_b32_e32 v236, v236, v237, vcc
	v_and_b32_e32 v237, 0xffff0000, v162
	v_cndmask_b32_e64 v5, v237, v236, s[30:31]
	v_lshlrev_b32_e32 v236, 16, v166
	v_and_b32_e32 v237, 0xffff0000, v166
	v_cndmask_b32_e32 v236, v236, v237, vcc
	v_lshlrev_b32_e32 v237, 16, v163
	v_cndmask_b32_e64 v6, v237, v236, s[30:31]
	v_lshlrev_b32_e32 v236, 16, v167
	v_and_b32_e32 v237, 0xffff0000, v167
	v_cndmask_b32_e32 v236, v236, v237, vcc
	v_and_b32_e32 v237, 0xffff0000, v163
	v_cndmask_b32_e64 v7, v237, v236, s[30:31]
	s_waitcnt vmcnt(30)
	v_mul_f32_e32 v160, v32, v0
	v_fmac_f32_e32 v160, v33, v1
	v_fmac_f32_e32 v160, v34, v2
	v_fmac_f32_e32 v160, v35, v3
	v_fmac_f32_e32 v160, v36, v4
	v_fmac_f32_e32 v160, v37, v5
	v_fmac_f32_e32 v160, v38, v6
	v_fmac_f32_e32 v160, v39, v7
	s_cmp_lg_u32 s11, 0
	s_cbranch_scc1 .Lsd_n7
	s_cmp_lt_u32 s10, 1
	s_cbranch_scc1 .Lsd_n7
	v_mov_b32_e32 v237, 0
	v_mov_b32_e32 v236, v24
	v_lshl_add_u64 v[230:231], s[4:5], 0, v[236:237]
	s_sub_u32 s29, s10, 1
	s_lshl_b32 s29, s29, 12
	v_lshlrev_b32_e32 v236, 5, v22
	v_add_u32_e32 v236, s29, v236
	v_lshl_add_u64 v[232:233], s[22:23], 0, v[236:237]
	v_cmp_eq_u32_e32 vcc, 0, v23
	s_nop 1
	v_cndmask_b32_e32 v230, v230, v232, vcc
	v_cndmask_b32_e32 v231, v231, v233, vcc
	global_load_dwordx4 v[32:35], v[230:231], off
	global_load_dwordx4 v[36:39], v[230:231], off offset:16
	s_branch .Lsd_d8
.Lsd_n7:
	global_load_dwordx4 v[32:35], v24, s[4:5] nt
	global_load_dwordx4 v[36:39], v24, s[4:5] offset:16 nt

.Lsd_n9:
	global_load_dwordx4 v[40:43], v25, s[4:5] nt
	global_load_dwordx4 v[44:47], v25, s[4:5] offset:16 nt

.Lsd_n11:
	global_load_dwordx4 v[48:51], v26, s[4:5] nt
	global_load_dwordx4 v[52:55], v26, s[4:5] offset:16 nt
.Lsd_d12:
	s_waitcnt vmcnt(30)
	v_mul_f32_e32 v163, v56, v0
	v_fmac_f32_e32 v163, v57, v1
	v_fmac_f32_e32 v163, v58, v2
	v_fmac_f32_e32 v163, v59, v3
	v_fmac_f32_e32 v163, v60, v4
	v_fmac_f32_e32 v163, v61, v5
	v_fmac_f32_e32 v163, v62, v6
	v_fmac_f32_e32 v163, v63, v7
	global_load_dwordx4 v[56:59], v27, s[4:5] nt
	global_load_dwordx4 v[60:63], v27, s[4:5] offset:16 nt
	s_waitcnt vmcnt(30)
	v_mul_f32_e32 v164, v64, v0
	v_fmac_f32_e32 v164, v65, v1
	v_fmac_f32_e32 v164, v66, v2
	v_fmac_f32_e32 v164, v67, v3
	v_fmac_f32_e32 v164, v68, v4
	v_fmac_f32_e32 v164, v69, v5
	v_fmac_f32_e32 v164, v70, v6
	v_fmac_f32_e32 v164, v71, v7
	global_load_dwordx4 v[64:67], v28, s[4:5] nt
	global_load_dwordx4 v[68:71], v28, s[4:5] offset:16 nt
	s_waitcnt vmcnt(30)
	v_mul_f32_e32 v165, v72, v0
	v_fmac_f32_e32 v165, v73, v1
	v_fmac_f32_e32 v165, v74, v2
	v_fmac_f32_e32 v165, v75, v3
	v_fmac_f32_e32 v165, v76, v4
	v_fmac_f32_e32 v165, v77, v5
	v_fmac_f32_e32 v165, v78, v6
	v_fmac_f32_e32 v165, v79, v7
	global_load_dwordx4 v[72:75], v29, s[4:5] nt
	global_load_dwordx4 v[76:79], v29, s[4:5] offset:16 nt
	s_waitcnt vmcnt(30)
	v_mul_f32_e32 v166, v80, v0
	v_fmac_f32_e32 v166, v81, v1
	v_fmac_f32_e32 v166, v82, v2
	v_fmac_f32_e32 v166, v83, v3
	v_fmac_f32_e32 v166, v84, v4
	v_fmac_f32_e32 v166, v85, v5
	v_fmac_f32_e32 v166, v86, v6
	v_fmac_f32_e32 v166, v87, v7
	global_load_dwordx4 v[80:83], v30, s[4:5] nt
	global_load_dwordx4 v[84:87], v30, s[4:5] offset:16 nt
	s_waitcnt vmcnt(30)
	v_mul_f32_e32 v167, v88, v0
	v_fmac_f32_e32 v167, v89, v1
	v_fmac_f32_e32 v167, v90, v2
	v_fmac_f32_e32 v167, v91, v3
	v_fmac_f32_e32 v167, v92, v4
	v_fmac_f32_e32 v167, v93, v5
	v_fmac_f32_e32 v167, v94, v6
	v_fmac_f32_e32 v167, v95, v7
	global_load_dwordx4 v[88:91], v31, s[4:5] nt
	global_load_dwordx4 v[92:95], v31, s[4:5] offset:16 nt
	s_waitcnt vmcnt(30)
	v_mul_f32_e32 v168, v96, v0
	v_fmac_f32_e32 v168, v97, v1
	v_fmac_f32_e32 v168, v98, v2
	v_fmac_f32_e32 v168, v99, v3
	v_fmac_f32_e32 v168, v100, v4
	v_fmac_f32_e32 v168, v101, v5
	v_fmac_f32_e32 v168, v102, v6
	v_fmac_f32_e32 v168, v103, v7
	global_load_dwordx4 v[96:99], v244, s[4:5] nt
	global_load_dwordx4 v[100:103], v244, s[4:5] offset:16 nt
	s_waitcnt vmcnt(30)
	v_mul_f32_e32 v169, v104, v0
	v_fmac_f32_e32 v169, v105, v1
	v_fmac_f32_e32 v169, v106, v2
	v_fmac_f32_e32 v169, v107, v3
	v_fmac_f32_e32 v169, v108, v4
	v_fmac_f32_e32 v169, v109, v5
	v_fmac_f32_e32 v169, v110, v6
	v_fmac_f32_e32 v169, v111, v7
	global_load_dwordx4 v[104:107], v245, s[4:5] nt
	global_load_dwordx4 v[108:111], v245, s[4:5] offset:16 nt
	s_waitcnt vmcnt(30)
	v_mul_f32_e32 v170, v112, v0
	v_fmac_f32_e32 v170, v113, v1
	v_fmac_f32_e32 v170, v114, v2
	v_fmac_f32_e32 v170, v115, v3
	v_fmac_f32_e32 v170, v116, v4
	v_fmac_f32_e32 v170, v117, v5
	v_fmac_f32_e32 v170, v118, v6
	v_fmac_f32_e32 v170, v119, v7
	global_load_dwordx4 v[112:115], v246, s[4:5] nt
	global_load_dwordx4 v[116:119], v246, s[4:5] offset:16 nt
	s_waitcnt vmcnt(30)
	v_mul_f32_e32 v171, v120, v0
	v_fmac_f32_e32 v171, v121, v1
	v_fmac_f32_e32 v171, v122, v2
	v_fmac_f32_e32 v171, v123, v3
	v_fmac_f32_e32 v171, v124, v4
	v_fmac_f32_e32 v171, v125, v5
	v_fmac_f32_e32 v171, v126, v6
	v_fmac_f32_e32 v171, v127, v7
	global_load_dwordx4 v[120:123], v247, s[4:5] nt
	global_load_dwordx4 v[124:127], v247, s[4:5] offset:16 nt
	s_waitcnt vmcnt(30)
	v_mul_f32_e32 v172, v128, v0
	v_fmac_f32_e32 v172, v129, v1
	v_fmac_f32_e32 v172, v130, v2
	v_fmac_f32_e32 v172, v131, v3
	v_fmac_f32_e32 v172, v132, v4
	v_fmac_f32_e32 v172, v133, v5
	v_fmac_f32_e32 v172, v134, v6
	v_fmac_f32_e32 v172, v135, v7
	global_load_dwordx4 v[128:131], v248, s[4:5] nt
	global_load_dwordx4 v[132:135], v248, s[4:5] offset:16 nt
	s_waitcnt vmcnt(30)
	v_mul_f32_e32 v173, v136, v0
	v_fmac_f32_e32 v173, v137, v1
	v_fmac_f32_e32 v173, v138, v2
	v_fmac_f32_e32 v173, v139, v3
	v_fmac_f32_e32 v173, v140, v4
	v_fmac_f32_e32 v173, v141, v5
	v_fmac_f32_e32 v173, v142, v6
	v_fmac_f32_e32 v173, v143, v7
	global_load_dwordx4 v[136:139], v249, s[4:5] nt
	global_load_dwordx4 v[140:143], v249, s[4:5] offset:16 nt
	s_waitcnt vmcnt(30)
	v_mul_f32_e32 v174, v144, v0
	v_fmac_f32_e32 v174, v145, v1
	v_fmac_f32_e32 v174, v146, v2
	v_fmac_f32_e32 v174, v147, v3
	v_fmac_f32_e32 v174, v148, v4
	v_fmac_f32_e32 v174, v149, v5
	v_fmac_f32_e32 v174, v150, v6
	v_fmac_f32_e32 v174, v151, v7
	global_load_dwordx4 v[144:147], v250, s[4:5] nt
	global_load_dwordx4 v[148:151], v250, s[4:5] offset:16 nt
	s_waitcnt vmcnt(30)
	v_mul_f32_e32 v175, v152, v0
	v_fmac_f32_e32 v175, v153, v1
	v_fmac_f32_e32 v175, v154, v2
	v_fmac_f32_e32 v175, v155, v3
	v_fmac_f32_e32 v175, v156, v4
	v_fmac_f32_e32 v175, v157, v5
	v_fmac_f32_e32 v175, v158, v6
	v_fmac_f32_e32 v175, v159, v7
	global_load_dwordx4 v[152:155], v251, s[4:5] nt
	global_load_dwordx4 v[156:159], v251, s[4:5] offset:16 nt
	v_add_f32_dpp v160, v160, v160 row_ror:8 row_mask:0xf bank_mask:0x3
	v_add_f32_dpp v160, v168, v168 row_ror:8 row_mask:0xf bank_mask:0xc
	v_add_f32_dpp v161, v161, v161 row_ror:8 row_mask:0xf bank_mask:0x3
	v_add_f32_dpp v161, v169, v169 row_ror:8 row_mask:0xf bank_mask:0xc
	v_add_f32_dpp v162, v162, v162 row_ror:8 row_mask:0xf bank_mask:0x3
	v_add_f32_dpp v162, v170, v170 row_ror:8 row_mask:0xf bank_mask:0xc
	v_add_f32_dpp v163, v163, v163 row_ror:8 row_mask:0xf bank_mask:0x3
	v_add_f32_dpp v163, v171, v171 row_ror:8 row_mask:0xf bank_mask:0xc
	v_add_f32_dpp v164, v164, v164 row_ror:8 row_mask:0xf bank_mask:0x3
	v_add_f32_dpp v164, v172, v172 row_ror:8 row_mask:0xf bank_mask:0xc
	v_add_f32_dpp v165, v165, v165 row_ror:8 row_mask:0xf bank_mask:0x3
	v_add_f32_dpp v165, v173, v173 row_ror:8 row_mask:0xf bank_mask:0xc
	v_add_f32_dpp v166, v166, v166 row_ror:8 row_mask:0xf bank_mask:0x3
	v_add_f32_dpp v166, v174, v174 row_ror:8 row_mask:0xf bank_mask:0xc
	v_add_f32_dpp v167, v167, v167 row_ror:8 row_mask:0xf bank_mask:0x3
	v_add_f32_dpp v167, v175, v175 row_ror:8 row_mask:0xf bank_mask:0xc
	v_add_f32_dpp v160, v160, v160 row_shl:4 row_mask:0xf bank_mask:0x5
	v_add_f32_dpp v160, v164, v164 row_shr:4 row_mask:0xf bank_mask:0xa
	v_add_f32_dpp v161, v161, v161 row_shl:4 row_mask:0xf bank_mask:0x5
	v_add_f32_dpp v161, v165, v165 row_shr:4 row_mask:0xf bank_mask:0xa
	v_add_f32_dpp v162, v162, v162 row_shl:4 row_mask:0xf bank_mask:0x5
	v_add_f32_dpp v162, v166, v166 row_shr:4 row_mask:0xf bank_mask:0xa
	v_add_f32_dpp v163, v163, v163 row_shl:4 row_mask:0xf bank_mask:0x5
	v_add_f32_dpp v163, v167, v167 row_shr:4 row_mask:0xf bank_mask:0xa
	v_and_b32_e32 v176, 2, v18
	v_cmp_ne_u32_e32 vcc, 0, v176
	v_add_f32_dpp v230, v160, v160 quad_perm:[2,3,0,1] row_mask:0xf bank_mask:0xf
	v_add_f32_dpp v231, v162, v162 quad_perm:[2,3,0,1] row_mask:0xf bank_mask:0xf
	v_add_f32_dpp v232, v161, v161 quad_perm:[2,3,0,1] row_mask:0xf bank_mask:0xf
	v_add_f32_dpp v233, v163, v163 quad_perm:[2,3,0,1] row_mask:0xf bank_mask:0xf
	v_cndmask_b32_e32 v230, v230, v231, vcc
	v_cndmask_b32_e32 v232, v232, v233, vcc
	v_and_b32_e32 v176, 1, v18
	v_cmp_ne_u32_e32 vcc, 0, v176
	v_add_f32_dpp v231, v230, v230 quad_perm:[1,0,3,2] row_mask:0xf bank_mask:0xf
	v_add_f32_dpp v233, v232, v232 quad_perm:[1,0,3,2] row_mask:0xf bank_mask:0xf
	s_nop 1
	v_cndmask_b32_e32 v241, v231, v233, vcc
	s_nop 1
	v_max_f32_dpp v242, v241, v241 row_ror:8 row_mask:0xf bank_mask:0xf
	s_nop 1
	v_max_f32_dpp v242, v242, v242 row_ror:4 row_mask:0xf bank_mask:0xf
	s_nop 1
	v_max_f32_dpp v242, v242, v242 row_ror:2 row_mask:0xf bank_mask:0xf
	s_nop 1
	v_max_f32_dpp v242, v242, v242 row_ror:1 row_mask:0xf bank_mask:0xf
	ds_bpermute_b32 v234, v238, v242
	s_waitcnt lgkmcnt(0)
	v_max_f32_e32 v242, v242, v234
	ds_bpermute_b32 v234, v239, v242
	s_waitcnt lgkmcnt(0)
	v_max_f32_e32 v242, v242, v234
	v_max_f32_e32 v242, v16, v242
	v_sub_f32_e32 v243, v16, v242
	v_sub_f32_e32 v240, v241, v242
	v_mul_f32_e32 v243, 0x3fb8aa3b, v243
	v_mul_f32_e32 v240, 0x3fb8aa3b, v240
	v_exp_f32_e32 v243, v243
	v_exp_f32_e32 v240, v240
	v_mov_b32_e32 v16, v242
	s_nop 0
	s_nop 1
	v_add_f32_dpp v235, v240, v240 row_ror:8 row_mask:0xf bank_mask:0xf
	s_nop 1
	v_add_f32_dpp v235, v235, v235 row_ror:4 row_mask:0xf bank_mask:0xf
	s_nop 1
	v_add_f32_dpp v235, v235, v235 row_ror:2 row_mask:0xf bank_mask:0xf
	s_nop 1
	v_add_f32_dpp v235, v235, v235 row_ror:1 row_mask:0xf bank_mask:0xf
	ds_bpermute_b32 v234, v238, v235
	s_waitcnt lgkmcnt(0)
	v_add_f32_e32 v235, v235, v234
	ds_bpermute_b32 v234, v239, v235
	s_waitcnt lgkmcnt(0)
	v_add_f32_e32 v235, v235, v234
	v_fma_f32 v17, v17, v243, v235
	v_mul_f32_e32 v8, v8, v243
	v_mul_f32_e32 v9, v9, v243
	v_mul_f32_e32 v10, v10, v243
	v_mul_f32_e32 v11, v11, v243
	v_mul_f32_e32 v12, v12, v243
	v_mul_f32_e32 v13, v13, v243
	v_mul_f32_e32 v14, v14, v243
	v_mul_f32_e32 v15, v15, v243
	s_add_u32 s27, s27, 1
	s_lshl_b32 s24, s27, 6
	s_lshr_b32 s28, s24, 7
	s_and_b32 s24, s24, 64
	s_lshl_b32 s28, s28, 1
	s_add_u32 s28, s28, 12
	s_lshl_b32 s25, 1, s28
	s_add_u32 s24, s24, 64
	s_lshl_b32 s24, s24, s28
	s_add_u32 s26, s10, 0x800
	s_lshl_b32 s26, s26, 12
	s_sub_u32 s26, s26, s24
	s_add_u32 s2, s16, s26
	s_addc_u32 s3, s17, 0
	s_add_u32 s4, s18, s26
	s_addc_u32 s5, s19, 0
	v_lshlrev_b32_e32 v24, 4, v23
	v_sub_u32_e32 v24, 63, v24
	v_lshlrev_b32_e32 v24, s28, v24
	v_lshl_add_u32 v24, v22, 5, v24
	v_subrev_u32_e32 v25, s25, v24
	v_subrev_u32_e32 v26, s25, v25
	v_subrev_u32_e32 v27, s25, v26
	v_subrev_u32_e32 v28, s25, v27
	v_subrev_u32_e32 v29, s25, v28
	v_subrev_u32_e32 v30, s25, v29
	v_subrev_u32_e32 v31, s25, v30
	v_subrev_u32_e32 v244, s25, v31
	v_subrev_u32_e32 v245, s25, v244
	v_subrev_u32_e32 v246, s25, v245
	v_subrev_u32_e32 v247, s25, v246
	v_subrev_u32_e32 v248, s25, v247
	v_subrev_u32_e32 v249, s25, v248
	v_subrev_u32_e32 v250, s25, v249
	v_subrev_u32_e32 v251, s25, v250
	s_waitcnt vmcnt(30)
	v_fmac_f32_dpp v8, v240, v32 row_newbcast:0 row_mask:0xf bank_mask:0xf
	v_fmac_f32_dpp v9, v240, v33 row_newbcast:0 row_mask:0xf bank_mask:0xf
	v_fmac_f32_dpp v10, v240, v34 row_newbcast:0 row_mask:0xf bank_mask:0xf
	v_fmac_f32_dpp v11, v240, v35 row_newbcast:0 row_mask:0xf bank_mask:0xf
	v_fmac_f32_dpp v12, v240, v36 row_newbcast:0 row_mask:0xf bank_mask:0xf
	v_fmac_f32_dpp v13, v240, v37 row_newbcast:0 row_mask:0xf bank_mask:0xf
	v_fmac_f32_dpp v14, v240, v38 row_newbcast:0 row_mask:0xf bank_mask:0xf
	v_fmac_f32_dpp v15, v240, v39 row_newbcast:0 row_mask:0xf bank_mask:0xf
	global_load_dwordx4 v[32:35], v24, s[2:3] nt
	global_load_dwordx4 v[36:39], v24, s[2:3] offset:16 nt
	s_waitcnt vmcnt(30)
	v_fmac_f32_dpp v8, v240, v40 row_newbcast:1 row_mask:0xf bank_mask:0xf
	v_fmac_f32_dpp v9, v240, v41 row_newbcast:1 row_mask:0xf bank_mask:0xf
	v_fmac_f32_dpp v10, v240, v42 row_newbcast:1 row_mask:0xf bank_mask:0xf
	v_fmac_f32_dpp v11, v240, v43 row_newbcast:1 row_mask:0xf bank_mask:0xf
	v_fmac_f32_dpp v12, v240, v44 row_newbcast:1 row_mask:0xf bank_mask:0xf
	v_fmac_f32_dpp v13, v240, v45 row_newbcast:1 row_mask:0xf bank_mask:0xf
	v_fmac_f32_dpp v14, v240, v46 row_newbcast:1 row_mask:0xf bank_mask:0xf
	v_fmac_f32_dpp v15, v240, v47 row_newbcast:1 row_mask:0xf bank_mask:0xf
	global_load_dwordx4 v[40:43], v25, s[2:3] nt
	global_load_dwordx4 v[44:47], v25, s[2:3] offset:16 nt
	s_waitcnt vmcnt(30)
	v_fmac_f32_dpp v8, v240, v48 row_newbcast:2 row_mask:0xf bank_mask:0xf
	v_fmac_f32_dpp v9, v240, v49 row_newbcast:2 row_mask:0xf bank_mask:0xf
	v_fmac_f32_dpp v10, v240, v50 row_newbcast:2 row_mask:0xf bank_mask:0xf
	v_fmac_f32_dpp v11, v240, v51 row_newbcast:2 row_mask:0xf bank_mask:0xf
	v_fmac_f32_dpp v12, v240, v52 row_newbcast:2 row_mask:0xf bank_mask:0xf
	v_fmac_f32_dpp v13, v240, v53 row_newbcast:2 row_mask:0xf bank_mask:0xf
	v_fmac_f32_dpp v14, v240, v54 row_newbcast:2 row_mask:0xf bank_mask:0xf
	v_fmac_f32_dpp v15, v240, v55 row_newbcast:2 row_mask:0xf bank_mask:0xf
	global_load_dwordx4 v[48:51], v26, s[2:3] nt
	global_load_dwordx4 v[52:55], v26, s[2:3] offset:16 nt
	s_waitcnt vmcnt(30)
	v_fmac_f32_dpp v8, v240, v56 row_newbcast:3 row_mask:0xf bank_mask:0xf
	v_fmac_f32_dpp v9, v240, v57 row_newbcast:3 row_mask:0xf bank_mask:0xf
	v_fmac_f32_dpp v10, v240, v58 row_newbcast:3 row_mask:0xf bank_mask:0xf
	v_fmac_f32_dpp v11, v240, v59 row_newbcast:3 row_mask:0xf bank_mask:0xf
	v_fmac_f32_dpp v12, v240, v60 row_newbcast:3 row_mask:0xf bank_mask:0xf
	v_fmac_f32_dpp v13, v240, v61 row_newbcast:3 row_mask:0xf bank_mask:0xf
	v_fmac_f32_dpp v14, v240, v62 row_newbcast:3 row_mask:0xf bank_mask:0xf
	v_fmac_f32_dpp v15, v240, v63 row_newbcast:3 row_mask:0xf bank_mask:0xf
	global_load_dwordx4 v[56:59], v27, s[2:3] nt
	global_load_dwordx4 v[60:63], v27, s[2:3] offset:16 nt
	s_waitcnt vmcnt(30)
	v_fmac_f32_dpp v8, v240, v64 row_newbcast:4 row_mask:0xf bank_mask:0xf
	v_fmac_f32_dpp v9, v240, v65 row_newbcast:4 row_mask:0xf bank_mask:0xf
	v_fmac_f32_dpp v10, v240, v66 row_newbcast:4 row_mask:0xf bank_mask:0xf
	v_fmac_f32_dpp v11, v240, v67 row_newbcast:4 row_mask:0xf bank_mask:0xf
	v_fmac_f32_dpp v12, v240, v68 row_newbcast:4 row_mask:0xf bank_mask:0xf
	v_fmac_f32_dpp v13, v240, v69 row_newbcast:4 row_mask:0xf bank_mask:0xf
	v_fmac_f32_dpp v14, v240, v70 row_newbcast:4 row_mask:0xf bank_mask:0xf
	v_fmac_f32_dpp v15, v240, v71 row_newbcast:4 row_mask:0xf bank_mask:0xf
	global_load_dwordx4 v[64:67], v28, s[2:3] nt
	global_load_dwordx4 v[68:71], v28, s[2:3] offset:16 nt
	s_waitcnt vmcnt(30)
	v_fmac_f32_dpp v8, v240, v72 row_newbcast:5 row_mask:0xf bank_mask:0xf
	v_fmac_f32_dpp v9, v240, v73 row_newbcast:5 row_mask:0xf bank_mask:0xf
	v_fmac_f32_dpp v10, v240, v74 row_newbcast:5 row_mask:0xf bank_mask:0xf
	v_fmac_f32_dpp v11, v240, v75 row_newbcast:5 row_mask:0xf bank_mask:0xf
	v_fmac_f32_dpp v12, v240, v76 row_newbcast:5 row_mask:0xf bank_mask:0xf
	v_fmac_f32_dpp v13, v240, v77 row_newbcast:5 row_mask:0xf bank_mask:0xf
	v_fmac_f32_dpp v14, v240, v78 row_newbcast:5 row_mask:0xf bank_mask:0xf
	v_fmac_f32_dpp v15, v240, v79 row_newbcast:5 row_mask:0xf bank_mask:0xf
	global_load_dwordx4 v[72:75], v29, s[2:3] nt
	global_load_dwordx4 v[76:79], v29, s[2:3] offset:16 nt
	s_waitcnt vmcnt(30)
	v_fmac_f32_dpp v8, v240, v80 row_newbcast:6 row_mask:0xf bank_mask:0xf
	v_fmac_f32_dpp v9, v240, v81 row_newbcast:6 row_mask:0xf bank_mask:0xf
	v_fmac_f32_dpp v10, v240, v82 row_newbcast:6 row_mask:0xf bank_mask:0xf
	v_fmac_f32_dpp v11, v240, v83 row_newbcast:6 row_mask:0xf bank_mask:0xf
	v_fmac_f32_dpp v12, v240, v84 row_newbcast:6 row_mask:0xf bank_mask:0xf
	v_fmac_f32_dpp v13, v240, v85 row_newbcast:6 row_mask:0xf bank_mask:0xf
	v_fmac_f32_dpp v14, v240, v86 row_newbcast:6 row_mask:0xf bank_mask:0xf
	v_fmac_f32_dpp v15, v240, v87 row_newbcast:6 row_mask:0xf bank_mask:0xf
	global_load_dwordx4 v[80:83], v30, s[2:3] nt
	global_load_dwordx4 v[84:87], v30, s[2:3] offset:16 nt
	s_waitcnt vmcnt(30)
	v_fmac_f32_dpp v8, v240, v88 row_newbcast:7 row_mask:0xf bank_mask:0xf
	v_fmac_f32_dpp v9, v240, v89 row_newbcast:7 row_mask:0xf bank_mask:0xf
	v_fmac_f32_dpp v10, v240, v90 row_newbcast:7 row_mask:0xf bank_mask:0xf
	v_fmac_f32_dpp v11, v240, v91 row_newbcast:7 row_mask:0xf bank_mask:0xf
	v_fmac_f32_dpp v12, v240, v92 row_newbcast:7 row_mask:0xf bank_mask:0xf
	v_fmac_f32_dpp v13, v240, v93 row_newbcast:7 row_mask:0xf bank_mask:0xf
	v_fmac_f32_dpp v14, v240, v94 row_newbcast:7 row_mask:0xf bank_mask:0xf
	v_fmac_f32_dpp v15, v240, v95 row_newbcast:7 row_mask:0xf bank_mask:0xf
	global_load_dwordx4 v[88:91], v31, s[2:3] nt
	global_load_dwordx4 v[92:95], v31, s[2:3] offset:16 nt
	s_waitcnt vmcnt(30)
	v_fmac_f32_dpp v8, v240, v96 row_newbcast:8 row_mask:0xf bank_mask:0xf
	v_fmac_f32_dpp v9, v240, v97 row_newbcast:8 row_mask:0xf bank_mask:0xf
	v_fmac_f32_dpp v10, v240, v98 row_newbcast:8 row_mask:0xf bank_mask:0xf
	v_fmac_f32_dpp v11, v240, v99 row_newbcast:8 row_mask:0xf bank_mask:0xf
	v_fmac_f32_dpp v12, v240, v100 row_newbcast:8 row_mask:0xf bank_mask:0xf
	v_fmac_f32_dpp v13, v240, v101 row_newbcast:8 row_mask:0xf bank_mask:0xf
	v_fmac_f32_dpp v14, v240, v102 row_newbcast:8 row_mask:0xf bank_mask:0xf
	v_fmac_f32_dpp v15, v240, v103 row_newbcast:8 row_mask:0xf bank_mask:0xf
	global_load_dwordx4 v[96:99], v244, s[2:3] nt
	global_load_dwordx4 v[100:103], v244, s[2:3] offset:16 nt
	s_waitcnt vmcnt(30)
	v_fmac_f32_dpp v8, v240, v104 row_newbcast:9 row_mask:0xf bank_mask:0xf
	v_fmac_f32_dpp v9, v240, v105 row_newbcast:9 row_mask:0xf bank_mask:0xf
	v_fmac_f32_dpp v10, v240, v106 row_newbcast:9 row_mask:0xf bank_mask:0xf
	v_fmac_f32_dpp v11, v240, v107 row_newbcast:9 row_mask:0xf bank_mask:0xf
	v_fmac_f32_dpp v12, v240, v108 row_newbcast:9 row_mask:0xf bank_mask:0xf
	v_fmac_f32_dpp v13, v240, v109 row_newbcast:9 row_mask:0xf bank_mask:0xf
	v_fmac_f32_dpp v14, v240, v110 row_newbcast:9 row_mask:0xf bank_mask:0xf
	v_fmac_f32_dpp v15, v240, v111 row_newbcast:9 row_mask:0xf bank_mask:0xf
	global_load_dwordx4 v[104:107], v245, s[2:3] nt
	global_load_dwordx4 v[108:111], v245, s[2:3] offset:16 nt
	s_waitcnt vmcnt(30)
	v_fmac_f32_dpp v8, v240, v112 row_newbcast:10 row_mask:0xf bank_mask:0xf
	v_fmac_f32_dpp v9, v240, v113 row_newbcast:10 row_mask:0xf bank_mask:0xf
	v_fmac_f32_dpp v10, v240, v114 row_newbcast:10 row_mask:0xf bank_mask:0xf
	v_fmac_f32_dpp v11, v240, v115 row_newbcast:10 row_mask:0xf bank_mask:0xf
	v_fmac_f32_dpp v12, v240, v116 row_newbcast:10 row_mask:0xf bank_mask:0xf
	v_fmac_f32_dpp v13, v240, v117 row_newbcast:10 row_mask:0xf bank_mask:0xf
	v_fmac_f32_dpp v14, v240, v118 row_newbcast:10 row_mask:0xf bank_mask:0xf
	v_fmac_f32_dpp v15, v240, v119 row_newbcast:10 row_mask:0xf bank_mask:0xf
	global_load_dwordx4 v[112:115], v246, s[2:3] nt
	global_load_dwordx4 v[116:119], v246, s[2:3] offset:16 nt
	s_waitcnt vmcnt(30)
	v_fmac_f32_dpp v8, v240, v120 row_newbcast:11 row_mask:0xf bank_mask:0xf
	v_fmac_f32_dpp v9, v240, v121 row_newbcast:11 row_mask:0xf bank_mask:0xf
	v_fmac_f32_dpp v10, v240, v122 row_newbcast:11 row_mask:0xf bank_mask:0xf
	v_fmac_f32_dpp v11, v240, v123 row_newbcast:11 row_mask:0xf bank_mask:0xf
	v_fmac_f32_dpp v12, v240, v124 row_newbcast:11 row_mask:0xf bank_mask:0xf
	v_fmac_f32_dpp v13, v240, v125 row_newbcast:11 row_mask:0xf bank_mask:0xf
	v_fmac_f32_dpp v14, v240, v126 row_newbcast:11 row_mask:0xf bank_mask:0xf
	v_fmac_f32_dpp v15, v240, v127 row_newbcast:11 row_mask:0xf bank_mask:0xf
	global_load_dwordx4 v[120:123], v247, s[2:3] nt
	global_load_dwordx4 v[124:127], v247, s[2:3] offset:16 nt
	s_waitcnt vmcnt(30)
	v_fmac_f32_dpp v8, v240, v128 row_newbcast:12 row_mask:0xf bank_mask:0xf
	v_fmac_f32_dpp v9, v240, v129 row_newbcast:12 row_mask:0xf bank_mask:0xf
	v_fmac_f32_dpp v10, v240, v130 row_newbcast:12 row_mask:0xf bank_mask:0xf
	v_fmac_f32_dpp v11, v240, v131 row_newbcast:12 row_mask:0xf bank_mask:0xf
	v_fmac_f32_dpp v12, v240, v132 row_newbcast:12 row_mask:0xf bank_mask:0xf
	v_fmac_f32_dpp v13, v240, v133 row_newbcast:12 row_mask:0xf bank_mask:0xf
	v_fmac_f32_dpp v14, v240, v134 row_newbcast:12 row_mask:0xf bank_mask:0xf
	v_fmac_f32_dpp v15, v240, v135 row_newbcast:12 row_mask:0xf bank_mask:0xf
	global_load_dwordx4 v[128:131], v248, s[2:3] nt
	global_load_dwordx4 v[132:135], v248, s[2:3] offset:16 nt
	s_waitcnt vmcnt(30)
	v_fmac_f32_dpp v8, v240, v136 row_newbcast:13 row_mask:0xf bank_mask:0xf
	v_fmac_f32_dpp v9, v240, v137 row_newbcast:13 row_mask:0xf bank_mask:0xf
	v_fmac_f32_dpp v10, v240, v138 row_newbcast:13 row_mask:0xf bank_mask:0xf
	v_fmac_f32_dpp v11, v240, v139 row_newbcast:13 row_mask:0xf bank_mask:0xf
	v_fmac_f32_dpp v12, v240, v140 row_newbcast:13 row_mask:0xf bank_mask:0xf
	v_fmac_f32_dpp v13, v240, v141 row_newbcast:13 row_mask:0xf bank_mask:0xf
	v_fmac_f32_dpp v14, v240, v142 row_newbcast:13 row_mask:0xf bank_mask:0xf
	v_fmac_f32_dpp v15, v240, v143 row_newbcast:13 row_mask:0xf bank_mask:0xf
	global_load_dwordx4 v[136:139], v249, s[2:3] nt
	global_load_dwordx4 v[140:143], v249, s[2:3] offset:16 nt
	s_waitcnt vmcnt(30)
	v_fmac_f32_dpp v8, v240, v144 row_newbcast:14 row_mask:0xf bank_mask:0xf
	v_fmac_f32_dpp v9, v240, v145 row_newbcast:14 row_mask:0xf bank_mask:0xf
	v_fmac_f32_dpp v10, v240, v146 row_newbcast:14 row_mask:0xf bank_mask:0xf
	v_fmac_f32_dpp v11, v240, v147 row_newbcast:14 row_mask:0xf bank_mask:0xf
	v_fmac_f32_dpp v12, v240, v148 row_newbcast:14 row_mask:0xf bank_mask:0xf
	v_fmac_f32_dpp v13, v240, v149 row_newbcast:14 row_mask:0xf bank_mask:0xf
	v_fmac_f32_dpp v14, v240, v150 row_newbcast:14 row_mask:0xf bank_mask:0xf
	v_fmac_f32_dpp v15, v240, v151 row_newbcast:14 row_mask:0xf bank_mask:0xf
	global_load_dwordx4 v[144:147], v250, s[2:3] nt
	global_load_dwordx4 v[148:151], v250, s[2:3] offset:16 nt
	s_waitcnt vmcnt(30)
	v_fmac_f32_dpp v8, v240, v152 row_newbcast:15 row_mask:0xf bank_mask:0xf
	v_fmac_f32_dpp v9, v240, v153 row_newbcast:15 row_mask:0xf bank_mask:0xf
	v_fmac_f32_dpp v10, v240, v154 row_newbcast:15 row_mask:0xf bank_mask:0xf
	v_fmac_f32_dpp v11, v240, v155 row_newbcast:15 row_mask:0xf bank_mask:0xf
	v_fmac_f32_dpp v12, v240, v156 row_newbcast:15 row_mask:0xf bank_mask:0xf
	v_fmac_f32_dpp v13, v240, v157 row_newbcast:15 row_mask:0xf bank_mask:0xf
	v_fmac_f32_dpp v14, v240, v158 row_newbcast:15 row_mask:0xf bank_mask:0xf
	v_fmac_f32_dpp v15, v240, v159 row_newbcast:15 row_mask:0xf bank_mask:0xf
	global_load_dwordx4 v[152:155], v251, s[2:3] nt
	global_load_dwordx4 v[156:159], v251, s[2:3] offset:16 nt
	s_waitcnt vmcnt(30)
	v_mul_f32_e32 v160, v32, v0
	v_fmac_f32_e32 v160, v33, v1
	v_fmac_f32_e32 v160, v34, v2
	v_fmac_f32_e32 v160, v35, v3
	v_fmac_f32_e32 v160, v36, v4
	v_fmac_f32_e32 v160, v37, v5
	v_fmac_f32_e32 v160, v38, v6
	v_fmac_f32_e32 v160, v39, v7
	global_load_dwordx4 v[32:35], v24, s[4:5] nt
	global_load_dwordx4 v[36:39], v24, s[4:5] offset:16 nt
	s_waitcnt vmcnt(30)
	v_mul_f32_e32 v161, v40, v0
	v_fmac_f32_e32 v161, v41, v1
	v_fmac_f32_e32 v161, v42, v2
	v_fmac_f32_e32 v161, v43, v3
	v_fmac_f32_e32 v161, v44, v4
	v_fmac_f32_e32 v161, v45, v5
	v_fmac_f32_e32 v161, v46, v6
	v_fmac_f32_e32 v161, v47, v7
	global_load_dwordx4 v[40:43], v25, s[4:5] nt
	global_load_dwordx4 v[44:47], v25, s[4:5] offset:16 nt
	s_waitcnt vmcnt(30)
	v_mul_f32_e32 v162, v48, v0
	v_fmac_f32_e32 v162, v49, v1
	v_fmac_f32_e32 v162, v50, v2
	v_fmac_f32_e32 v162, v51, v3
	v_fmac_f32_e32 v162, v52, v4
	v_fmac_f32_e32 v162, v53, v5
	v_fmac_f32_e32 v162, v54, v6
	v_fmac_f32_e32 v162, v55, v7
	global_load_dwordx4 v[48:51], v26, s[4:5] nt
	global_load_dwordx4 v[52:55], v26, s[4:5] offset:16 nt
	s_waitcnt vmcnt(30)
	v_mul_f32_e32 v163, v56, v0
	v_fmac_f32_e32 v163, v57, v1
	v_fmac_f32_e32 v163, v58, v2
	v_fmac_f32_e32 v163, v59, v3
	v_fmac_f32_e32 v163, v60, v4
	v_fmac_f32_e32 v163, v61, v5
	v_fmac_f32_e32 v163, v62, v6
	v_fmac_f32_e32 v163, v63, v7
	global_load_dwordx4 v[56:59], v27, s[4:5] nt
	global_load_dwordx4 v[60:63], v27, s[4:5] offset:16 nt
	s_waitcnt vmcnt(30)
	v_mul_f32_e32 v164, v64, v0
	v_fmac_f32_e32 v164, v65, v1
	v_fmac_f32_e32 v164, v66, v2
	v_fmac_f32_e32 v164, v67, v3
	v_fmac_f32_e32 v164, v68, v4
	v_fmac_f32_e32 v164, v69, v5
	v_fmac_f32_e32 v164, v70, v6
	v_fmac_f32_e32 v164, v71, v7
	global_load_dwordx4 v[64:67], v28, s[4:5] nt
	global_load_dwordx4 v[68:71], v28, s[4:5] offset:16 nt
	s_waitcnt vmcnt(30)
	v_mul_f32_e32 v165, v72, v0
	v_fmac_f32_e32 v165, v73, v1
	v_fmac_f32_e32 v165, v74, v2
	v_fmac_f32_e32 v165, v75, v3
	v_fmac_f32_e32 v165, v76, v4
	v_fmac_f32_e32 v165, v77, v5
	v_fmac_f32_e32 v165, v78, v6
	v_fmac_f32_e32 v165, v79, v7
	global_load_dwordx4 v[72:75], v29, s[4:5] nt
	global_load_dwordx4 v[76:79], v29, s[4:5] offset:16 nt
	s_waitcnt vmcnt(30)
	v_mul_f32_e32 v166, v80, v0
	v_fmac_f32_e32 v166, v81, v1
	v_fmac_f32_e32 v166, v82, v2
	v_fmac_f32_e32 v166, v83, v3
	v_fmac_f32_e32 v166, v84, v4
	v_fmac_f32_e32 v166, v85, v5
	v_fmac_f32_e32 v166, v86, v6
	v_fmac_f32_e32 v166, v87, v7
	global_load_dwordx4 v[80:83], v30, s[4:5] nt
	global_load_dwordx4 v[84:87], v30, s[4:5] offset:16 nt
	s_waitcnt vmcnt(30)
	v_mul_f32_e32 v167, v88, v0
	v_fmac_f32_e32 v167, v89, v1
	v_fmac_f32_e32 v167, v90, v2
	v_fmac_f32_e32 v167, v91, v3
	v_fmac_f32_e32 v167, v92, v4
	v_fmac_f32_e32 v167, v93, v5
	v_fmac_f32_e32 v167, v94, v6
	v_fmac_f32_e32 v167, v95, v7
	global_load_dwordx4 v[88:91], v31, s[4:5] nt
	global_load_dwordx4 v[92:95], v31, s[4:5] offset:16 nt
	s_waitcnt vmcnt(30)
	v_mul_f32_e32 v168, v96, v0
	v_fmac_f32_e32 v168, v97, v1
	v_fmac_f32_e32 v168, v98, v2
	v_fmac_f32_e32 v168, v99, v3
	v_fmac_f32_e32 v168, v100, v4
	v_fmac_f32_e32 v168, v101, v5
	v_fmac_f32_e32 v168, v102, v6
	v_fmac_f32_e32 v168, v103, v7
	global_load_dwordx4 v[96:99], v244, s[4:5] nt
	global_load_dwordx4 v[100:103], v244, s[4:5] offset:16 nt
	s_waitcnt vmcnt(30)
	v_mul_f32_e32 v169, v104, v0
	v_fmac_f32_e32 v169, v105, v1
	v_fmac_f32_e32 v169, v106, v2
	v_fmac_f32_e32 v169, v107, v3
	v_fmac_f32_e32 v169, v108, v4
	v_fmac_f32_e32 v169, v109, v5
	v_fmac_f32_e32 v169, v110, v6
	v_fmac_f32_e32 v169, v111, v7
	global_load_dwordx4 v[104:107], v245, s[4:5] nt
	global_load_dwordx4 v[108:111], v245, s[4:5] offset:16 nt
	s_waitcnt vmcnt(30)
	v_mul_f32_e32 v170, v112, v0
	v_fmac_f32_e32 v170, v113, v1
	v_fmac_f32_e32 v170, v114, v2
	v_fmac_f32_e32 v170, v115, v3
	v_fmac_f32_e32 v170, v116, v4
	v_fmac_f32_e32 v170, v117, v5
	v_fmac_f32_e32 v170, v118, v6
	v_fmac_f32_e32 v170, v119, v7
	global_load_dwordx4 v[112:115], v246, s[4:5] nt
	global_load_dwordx4 v[116:119], v246, s[4:5] offset:16 nt
	s_waitcnt vmcnt(30)
	v_mul_f32_e32 v171, v120, v0
	v_fmac_f32_e32 v171, v121, v1
	v_fmac_f32_e32 v171, v122, v2
	v_fmac_f32_e32 v171, v123, v3
	v_fmac_f32_e32 v171, v124, v4
	v_fmac_f32_e32 v171, v125, v5
	v_fmac_f32_e32 v171, v126, v6
	v_fmac_f32_e32 v171, v127, v7
	global_load_dwordx4 v[120:123], v247, s[4:5] nt
	global_load_dwordx4 v[124:127], v247, s[4:5] offset:16 nt
	s_waitcnt vmcnt(30)
	v_mul_f32_e32 v172, v128, v0
	v_fmac_f32_e32 v172, v129, v1
	v_fmac_f32_e32 v172, v130, v2
	v_fmac_f32_e32 v172, v131, v3
	v_fmac_f32_e32 v172, v132, v4
	v_fmac_f32_e32 v172, v133, v5
	v_fmac_f32_e32 v172, v134, v6
	v_fmac_f32_e32 v172, v135, v7
	global_load_dwordx4 v[128:131], v248, s[4:5] nt
	global_load_dwordx4 v[132:135], v248, s[4:5] offset:16 nt
	s_waitcnt vmcnt(30)
	v_mul_f32_e32 v173, v136, v0
	v_fmac_f32_e32 v173, v137, v1
	v_fmac_f32_e32 v173, v138, v2
	v_fmac_f32_e32 v173, v139, v3
	v_fmac_f32_e32 v173, v140, v4
	v_fmac_f32_e32 v173, v141, v5
	v_fmac_f32_e32 v173, v142, v6
	v_fmac_f32_e32 v173, v143, v7
	global_load_dwordx4 v[136:139], v249, s[4:5] nt
	global_load_dwordx4 v[140:143], v249, s[4:5] offset:16 nt
	s_waitcnt vmcnt(30)
	v_mul_f32_e32 v174, v144, v0
	v_fmac_f32_e32 v174, v145, v1
	v_fmac_f32_e32 v174, v146, v2
	v_fmac_f32_e32 v174, v147, v3
	v_fmac_f32_e32 v174, v148, v4
	v_fmac_f32_e32 v174, v149, v5
	v_fmac_f32_e32 v174, v150, v6
	v_fmac_f32_e32 v174, v151, v7
	global_load_dwordx4 v[144:147], v250, s[4:5] nt
	global_load_dwordx4 v[148:151], v250, s[4:5] offset:16 nt
	s_waitcnt vmcnt(30)
	v_mul_f32_e32 v175, v152, v0
	v_fmac_f32_e32 v175, v153, v1
	v_fmac_f32_e32 v175, v154, v2
	v_fmac_f32_e32 v175, v155, v3
	v_fmac_f32_e32 v175, v156, v4
	v_fmac_f32_e32 v175, v157, v5
	v_fmac_f32_e32 v175, v158, v6
	v_fmac_f32_e32 v175, v159, v7
	global_load_dwordx4 v[152:155], v251, s[4:5] nt
	global_load_dwordx4 v[156:159], v251, s[4:5] offset:16 nt
	v_add_f32_dpp v160, v160, v160 row_ror:8 row_mask:0xf bank_mask:0x3
	v_add_f32_dpp v160, v168, v168 row_ror:8 row_mask:0xf bank_mask:0xc
	v_add_f32_dpp v161, v161, v161 row_ror:8 row_mask:0xf bank_mask:0x3
	v_add_f32_dpp v161, v169, v169 row_ror:8 row_mask:0xf bank_mask:0xc
	v_add_f32_dpp v162, v162, v162 row_ror:8 row_mask:0xf bank_mask:0x3
	v_add_f32_dpp v162, v170, v170 row_ror:8 row_mask:0xf bank_mask:0xc
	v_add_f32_dpp v163, v163, v163 row_ror:8 row_mask:0xf bank_mask:0x3
	v_add_f32_dpp v163, v171, v171 row_ror:8 row_mask:0xf bank_mask:0xc
	v_add_f32_dpp v164, v164, v164 row_ror:8 row_mask:0xf bank_mask:0x3
	v_add_f32_dpp v164, v172, v172 row_ror:8 row_mask:0xf bank_mask:0xc
	v_add_f32_dpp v165, v165, v165 row_ror:8 row_mask:0xf bank_mask:0x3
	v_add_f32_dpp v165, v173, v173 row_ror:8 row_mask:0xf bank_mask:0xc
	v_add_f32_dpp v166, v166, v166 row_ror:8 row_mask:0xf bank_mask:0x3
	v_add_f32_dpp v166, v174, v174 row_ror:8 row_mask:0xf bank_mask:0xc
	v_add_f32_dpp v167, v167, v167 row_ror:8 row_mask:0xf bank_mask:0x3
	v_add_f32_dpp v167, v175, v175 row_ror:8 row_mask:0xf bank_mask:0xc
	v_add_f32_dpp v160, v160, v160 row_shl:4 row_mask:0xf bank_mask:0x5
	v_add_f32_dpp v160, v164, v164 row_shr:4 row_mask:0xf bank_mask:0xa
	v_add_f32_dpp v161, v161, v161 row_shl:4 row_mask:0xf bank_mask:0x5
	v_add_f32_dpp v161, v165, v165 row_shr:4 row_mask:0xf bank_mask:0xa
	v_add_f32_dpp v162, v162, v162 row_shl:4 row_mask:0xf bank_mask:0x5
	v_add_f32_dpp v162, v166, v166 row_shr:4 row_mask:0xf bank_mask:0xa
	v_add_f32_dpp v163, v163, v163 row_shl:4 row_mask:0xf bank_mask:0x5
	v_add_f32_dpp v163, v167, v167 row_shr:4 row_mask:0xf bank_mask:0xa
	v_and_b32_e32 v176, 2, v18
	v_cmp_ne_u32_e32 vcc, 0, v176
	v_add_f32_dpp v230, v160, v160 quad_perm:[2,3,0,1] row_mask:0xf bank_mask:0xf
	v_add_f32_dpp v231, v162, v162 quad_perm:[2,3,0,1] row_mask:0xf bank_mask:0xf
	v_add_f32_dpp v232, v161, v161 quad_perm:[2,3,0,1] row_mask:0xf bank_mask:0xf
	v_add_f32_dpp v233, v163, v163 quad_perm:[2,3,0,1] row_mask:0xf bank_mask:0xf
	v_cndmask_b32_e32 v230, v230, v231, vcc
	v_cndmask_b32_e32 v232, v232, v233, vcc
	v_and_b32_e32 v176, 1, v18
	v_cmp_ne_u32_e32 vcc, 0, v176
	v_add_f32_dpp v231, v230, v230 quad_perm:[1,0,3,2] row_mask:0xf bank_mask:0xf
	v_add_f32_dpp v233, v232, v232 quad_perm:[1,0,3,2] row_mask:0xf bank_mask:0xf
	s_nop 1
	v_cndmask_b32_e32 v241, v231, v233, vcc
	s_nop 1
	v_max_f32_dpp v242, v241, v241 row_ror:8 row_mask:0xf bank_mask:0xf
	s_nop 1
	v_max_f32_dpp v242, v242, v242 row_ror:4 row_mask:0xf bank_mask:0xf
	s_nop 1
	v_max_f32_dpp v242, v242, v242 row_ror:2 row_mask:0xf bank_mask:0xf
	s_nop 1
	v_max_f32_dpp v242, v242, v242 row_ror:1 row_mask:0xf bank_mask:0xf
	ds_bpermute_b32 v234, v238, v242
	s_waitcnt lgkmcnt(0)
	v_max_f32_e32 v242, v242, v234
	ds_bpermute_b32 v234, v239, v242
	s_waitcnt lgkmcnt(0)
	v_max_f32_e32 v242, v242, v234
	v_max_f32_e32 v242, v16, v242
	v_sub_f32_e32 v243, v16, v242
	v_sub_f32_e32 v240, v241, v242
	v_mul_f32_e32 v243, 0x3fb8aa3b, v243
	v_mul_f32_e32 v240, 0x3fb8aa3b, v240
	v_exp_f32_e32 v243, v243
	v_exp_f32_e32 v240, v240
	v_mov_b32_e32 v16, v242
	s_nop 0
	s_nop 1
	v_add_f32_dpp v235, v240, v240 row_ror:8 row_mask:0xf bank_mask:0xf
	s_nop 1
	v_add_f32_dpp v235, v235, v235 row_ror:4 row_mask:0xf bank_mask:0xf
	s_nop 1
	v_add_f32_dpp v235, v235, v235 row_ror:2 row_mask:0xf bank_mask:0xf
	s_nop 1
	v_add_f32_dpp v235, v235, v235 row_ror:1 row_mask:0xf bank_mask:0xf
	ds_bpermute_b32 v234, v238, v235
	s_waitcnt lgkmcnt(0)
	v_add_f32_e32 v235, v235, v234
	ds_bpermute_b32 v234, v239, v235
	s_waitcnt lgkmcnt(0)
	v_add_f32_e32 v235, v235, v234
	v_fma_f32 v17, v17, v243, v235
	v_mul_f32_e32 v8, v8, v243
	v_mul_f32_e32 v9, v9, v243
	v_mul_f32_e32 v10, v10, v243
	v_mul_f32_e32 v11, v11, v243
	v_mul_f32_e32 v12, v12, v243
	v_mul_f32_e32 v13, v13, v243
	v_mul_f32_e32 v14, v14, v243
	v_mul_f32_e32 v15, v15, v243
	s_add_u32 s27, s27, 1
	s_lshl_b32 s24, s27, 6
	s_lshr_b32 s28, s24, 7
	s_and_b32 s24, s24, 64
	s_lshl_b32 s28, s28, 1
	s_add_u32 s28, s28, 12
	s_lshl_b32 s25, 1, s28
	s_add_u32 s24, s24, 64
	s_lshl_b32 s24, s24, s28
	s_add_u32 s26, s10, 0x800
	s_lshl_b32 s26, s26, 12
	s_sub_u32 s26, s26, s24
	s_add_u32 s2, s16, s26
	s_addc_u32 s3, s17, 0
	s_add_u32 s4, s18, s26
	s_addc_u32 s5, s19, 0
	v_lshlrev_b32_e32 v24, 4, v23
	v_sub_u32_e32 v24, 63, v24
	v_lshlrev_b32_e32 v24, s28, v24
	v_lshl_add_u32 v24, v22, 5, v24
	v_subrev_u32_e32 v25, s25, v24
	v_subrev_u32_e32 v26, s25, v25
	v_subrev_u32_e32 v27, s25, v26
	v_subrev_u32_e32 v28, s25, v27
	v_subrev_u32_e32 v29, s25, v28
	v_subrev_u32_e32 v30, s25, v29
	v_subrev_u32_e32 v31, s25, v30
	v_subrev_u32_e32 v244, s25, v31
	v_subrev_u32_e32 v245, s25, v244
	v_subrev_u32_e32 v246, s25, v245
	v_subrev_u32_e32 v247, s25, v246
	v_subrev_u32_e32 v248, s25, v247
	v_subrev_u32_e32 v249, s25, v248
	v_subrev_u32_e32 v250, s25, v249
	v_subrev_u32_e32 v251, s25, v250
	s_waitcnt vmcnt(30)
	v_fmac_f32_dpp v8, v240, v32 row_newbcast:0 row_mask:0xf bank_mask:0xf
	v_fmac_f32_dpp v9, v240, v33 row_newbcast:0 row_mask:0xf bank_mask:0xf
	v_fmac_f32_dpp v10, v240, v34 row_newbcast:0 row_mask:0xf bank_mask:0xf
	v_fmac_f32_dpp v11, v240, v35 row_newbcast:0 row_mask:0xf bank_mask:0xf
	v_fmac_f32_dpp v12, v240, v36 row_newbcast:0 row_mask:0xf bank_mask:0xf
	v_fmac_f32_dpp v13, v240, v37 row_newbcast:0 row_mask:0xf bank_mask:0xf
	v_fmac_f32_dpp v14, v240, v38 row_newbcast:0 row_mask:0xf bank_mask:0xf
	v_fmac_f32_dpp v15, v240, v39 row_newbcast:0 row_mask:0xf bank_mask:0xf
	global_load_dwordx4 v[32:35], v24, s[2:3] nt
	global_load_dwordx4 v[36:39], v24, s[2:3] offset:16 nt
	s_waitcnt vmcnt(30)
	v_fmac_f32_dpp v8, v240, v40 row_newbcast:1 row_mask:0xf bank_mask:0xf
	v_fmac_f32_dpp v9, v240, v41 row_newbcast:1 row_mask:0xf bank_mask:0xf
	v_fmac_f32_dpp v10, v240, v42 row_newbcast:1 row_mask:0xf bank_mask:0xf
	v_fmac_f32_dpp v11, v240, v43 row_newbcast:1 row_mask:0xf bank_mask:0xf
	v_fmac_f32_dpp v12, v240, v44 row_newbcast:1 row_mask:0xf bank_mask:0xf
	v_fmac_f32_dpp v13, v240, v45 row_newbcast:1 row_mask:0xf bank_mask:0xf
	v_fmac_f32_dpp v14, v240, v46 row_newbcast:1 row_mask:0xf bank_mask:0xf
	v_fmac_f32_dpp v15, v240, v47 row_newbcast:1 row_mask:0xf bank_mask:0xf
	global_load_dwordx4 v[40:43], v25, s[2:3] nt
	global_load_dwordx4 v[44:47], v25, s[2:3] offset:16 nt
	s_waitcnt vmcnt(30)
	v_fmac_f32_dpp v8, v240, v48 row_newbcast:2 row_mask:0xf bank_mask:0xf
	v_fmac_f32_dpp v9, v240, v49 row_newbcast:2 row_mask:0xf bank_mask:0xf
	v_fmac_f32_dpp v10, v240, v50 row_newbcast:2 row_mask:0xf bank_mask:0xf
	v_fmac_f32_dpp v11, v240, v51 row_newbcast:2 row_mask:0xf bank_mask:0xf
	v_fmac_f32_dpp v12, v240, v52 row_newbcast:2 row_mask:0xf bank_mask:0xf
	v_fmac_f32_dpp v13, v240, v53 row_newbcast:2 row_mask:0xf bank_mask:0xf
	v_fmac_f32_dpp v14, v240, v54 row_newbcast:2 row_mask:0xf bank_mask:0xf
	v_fmac_f32_dpp v15, v240, v55 row_newbcast:2 row_mask:0xf bank_mask:0xf
	global_load_dwordx4 v[48:51], v26, s[2:3] nt
	global_load_dwordx4 v[52:55], v26, s[2:3] offset:16 nt
	s_waitcnt vmcnt(30)
	v_fmac_f32_dpp v8, v240, v56 row_newbcast:3 row_mask:0xf bank_mask:0xf
	v_fmac_f32_dpp v9, v240, v57 row_newbcast:3 row_mask:0xf bank_mask:0xf
	v_fmac_f32_dpp v10, v240, v58 row_newbcast:3 row_mask:0xf bank_mask:0xf
	v_fmac_f32_dpp v11, v240, v59 row_newbcast:3 row_mask:0xf bank_mask:0xf
	v_fmac_f32_dpp v12, v240, v60 row_newbcast:3 row_mask:0xf bank_mask:0xf
	v_fmac_f32_dpp v13, v240, v61 row_newbcast:3 row_mask:0xf bank_mask:0xf
	v_fmac_f32_dpp v14, v240, v62 row_newbcast:3 row_mask:0xf bank_mask:0xf
	v_fmac_f32_dpp v15, v240, v63 row_newbcast:3 row_mask:0xf bank_mask:0xf
	global_load_dwordx4 v[56:59], v27, s[2:3] nt
	global_load_dwordx4 v[60:63], v27, s[2:3] offset:16 nt
	s_waitcnt vmcnt(30)
	v_fmac_f32_dpp v8, v240, v64 row_newbcast:4 row_mask:0xf bank_mask:0xf
	v_fmac_f32_dpp v9, v240, v65 row_newbcast:4 row_mask:0xf bank_mask:0xf
	v_fmac_f32_dpp v10, v240, v66 row_newbcast:4 row_mask:0xf bank_mask:0xf
	v_fmac_f32_dpp v11, v240, v67 row_newbcast:4 row_mask:0xf bank_mask:0xf
	v_fmac_f32_dpp v12, v240, v68 row_newbcast:4 row_mask:0xf bank_mask:0xf
	v_fmac_f32_dpp v13, v240, v69 row_newbcast:4 row_mask:0xf bank_mask:0xf
	v_fmac_f32_dpp v14, v240, v70 row_newbcast:4 row_mask:0xf bank_mask:0xf
	v_fmac_f32_dpp v15, v240, v71 row_newbcast:4 row_mask:0xf bank_mask:0xf
	global_load_dwordx4 v[64:67], v28, s[2:3] nt
	global_load_dwordx4 v[68:71], v28, s[2:3] offset:16 nt
	s_waitcnt vmcnt(30)
	v_fmac_f32_dpp v8, v240, v72 row_newbcast:5 row_mask:0xf bank_mask:0xf
	v_fmac_f32_dpp v9, v240, v73 row_newbcast:5 row_mask:0xf bank_mask:0xf
	v_fmac_f32_dpp v10, v240, v74 row_newbcast:5 row_mask:0xf bank_mask:0xf
	v_fmac_f32_dpp v11, v240, v75 row_newbcast:5 row_mask:0xf bank_mask:0xf
	v_fmac_f32_dpp v12, v240, v76 row_newbcast:5 row_mask:0xf bank_mask:0xf
	v_fmac_f32_dpp v13, v240, v77 row_newbcast:5 row_mask:0xf bank_mask:0xf
	v_fmac_f32_dpp v14, v240, v78 row_newbcast:5 row_mask:0xf bank_mask:0xf
	v_fmac_f32_dpp v15, v240, v79 row_newbcast:5 row_mask:0xf bank_mask:0xf
	global_load_dwordx4 v[72:75], v29, s[2:3] nt
	global_load_dwordx4 v[76:79], v29, s[2:3] offset:16 nt
	s_waitcnt vmcnt(30)
	v_fmac_f32_dpp v8, v240, v80 row_newbcast:6 row_mask:0xf bank_mask:0xf
	v_fmac_f32_dpp v9, v240, v81 row_newbcast:6 row_mask:0xf bank_mask:0xf
	v_fmac_f32_dpp v10, v240, v82 row_newbcast:6 row_mask:0xf bank_mask:0xf
	v_fmac_f32_dpp v11, v240, v83 row_newbcast:6 row_mask:0xf bank_mask:0xf
	v_fmac_f32_dpp v12, v240, v84 row_newbcast:6 row_mask:0xf bank_mask:0xf
	v_fmac_f32_dpp v13, v240, v85 row_newbcast:6 row_mask:0xf bank_mask:0xf
	v_fmac_f32_dpp v14, v240, v86 row_newbcast:6 row_mask:0xf bank_mask:0xf
	v_fmac_f32_dpp v15, v240, v87 row_newbcast:6 row_mask:0xf bank_mask:0xf
	global_load_dwordx4 v[80:83], v30, s[2:3] nt
	global_load_dwordx4 v[84:87], v30, s[2:3] offset:16 nt
	s_waitcnt vmcnt(30)
	v_fmac_f32_dpp v8, v240, v88 row_newbcast:7 row_mask:0xf bank_mask:0xf
	v_fmac_f32_dpp v9, v240, v89 row_newbcast:7 row_mask:0xf bank_mask:0xf
	v_fmac_f32_dpp v10, v240, v90 row_newbcast:7 row_mask:0xf bank_mask:0xf
	v_fmac_f32_dpp v11, v240, v91 row_newbcast:7 row_mask:0xf bank_mask:0xf
	v_fmac_f32_dpp v12, v240, v92 row_newbcast:7 row_mask:0xf bank_mask:0xf
	v_fmac_f32_dpp v13, v240, v93 row_newbcast:7 row_mask:0xf bank_mask:0xf
	v_fmac_f32_dpp v14, v240, v94 row_newbcast:7 row_mask:0xf bank_mask:0xf
	v_fmac_f32_dpp v15, v240, v95 row_newbcast:7 row_mask:0xf bank_mask:0xf
	global_load_dwordx4 v[88:91], v31, s[2:3] nt
	global_load_dwordx4 v[92:95], v31, s[2:3] offset:16 nt
	s_waitcnt vmcnt(30)
	v_fmac_f32_dpp v8, v240, v96 row_newbcast:8 row_mask:0xf bank_mask:0xf
	v_fmac_f32_dpp v9, v240, v97 row_newbcast:8 row_mask:0xf bank_mask:0xf
	v_fmac_f32_dpp v10, v240, v98 row_newbcast:8 row_mask:0xf bank_mask:0xf
	v_fmac_f32_dpp v11, v240, v99 row_newbcast:8 row_mask:0xf bank_mask:0xf
	v_fmac_f32_dpp v12, v240, v100 row_newbcast:8 row_mask:0xf bank_mask:0xf
	v_fmac_f32_dpp v13, v240, v101 row_newbcast:8 row_mask:0xf bank_mask:0xf
	v_fmac_f32_dpp v14, v240, v102 row_newbcast:8 row_mask:0xf bank_mask:0xf
	v_fmac_f32_dpp v15, v240, v103 row_newbcast:8 row_mask:0xf bank_mask:0xf
	global_load_dwordx4 v[96:99], v244, s[2:3] nt
	global_load_dwordx4 v[100:103], v244, s[2:3] offset:16 nt
	s_waitcnt vmcnt(30)
	v_fmac_f32_dpp v8, v240, v104 row_newbcast:9 row_mask:0xf bank_mask:0xf
	v_fmac_f32_dpp v9, v240, v105 row_newbcast:9 row_mask:0xf bank_mask:0xf
	v_fmac_f32_dpp v10, v240, v106 row_newbcast:9 row_mask:0xf bank_mask:0xf
	v_fmac_f32_dpp v11, v240, v107 row_newbcast:9 row_mask:0xf bank_mask:0xf
	v_fmac_f32_dpp v12, v240, v108 row_newbcast:9 row_mask:0xf bank_mask:0xf
	v_fmac_f32_dpp v13, v240, v109 row_newbcast:9 row_mask:0xf bank_mask:0xf
	v_fmac_f32_dpp v14, v240, v110 row_newbcast:9 row_mask:0xf bank_mask:0xf
	v_fmac_f32_dpp v15, v240, v111 row_newbcast:9 row_mask:0xf bank_mask:0xf
	global_load_dwordx4 v[104:107], v245, s[2:3] nt
	global_load_dwordx4 v[108:111], v245, s[2:3] offset:16 nt
	s_waitcnt vmcnt(30)
	v_fmac_f32_dpp v8, v240, v112 row_newbcast:10 row_mask:0xf bank_mask:0xf
	v_fmac_f32_dpp v9, v240, v113 row_newbcast:10 row_mask:0xf bank_mask:0xf
	v_fmac_f32_dpp v10, v240, v114 row_newbcast:10 row_mask:0xf bank_mask:0xf
	v_fmac_f32_dpp v11, v240, v115 row_newbcast:10 row_mask:0xf bank_mask:0xf
	v_fmac_f32_dpp v12, v240, v116 row_newbcast:10 row_mask:0xf bank_mask:0xf
	v_fmac_f32_dpp v13, v240, v117 row_newbcast:10 row_mask:0xf bank_mask:0xf
	v_fmac_f32_dpp v14, v240, v118 row_newbcast:10 row_mask:0xf bank_mask:0xf
	v_fmac_f32_dpp v15, v240, v119 row_newbcast:10 row_mask:0xf bank_mask:0xf
	global_load_dwordx4 v[112:115], v246, s[2:3] nt
	global_load_dwordx4 v[116:119], v246, s[2:3] offset:16 nt
	s_waitcnt vmcnt(30)
	v_fmac_f32_dpp v8, v240, v120 row_newbcast:11 row_mask:0xf bank_mask:0xf
	v_fmac_f32_dpp v9, v240, v121 row_newbcast:11 row_mask:0xf bank_mask:0xf
	v_fmac_f32_dpp v10, v240, v122 row_newbcast:11 row_mask:0xf bank_mask:0xf
	v_fmac_f32_dpp v11, v240, v123 row_newbcast:11 row_mask:0xf bank_mask:0xf
	v_fmac_f32_dpp v12, v240, v124 row_newbcast:11 row_mask:0xf bank_mask:0xf
	v_fmac_f32_dpp v13, v240, v125 row_newbcast:11 row_mask:0xf bank_mask:0xf
	v_fmac_f32_dpp v14, v240, v126 row_newbcast:11 row_mask:0xf bank_mask:0xf
	v_fmac_f32_dpp v15, v240, v127 row_newbcast:11 row_mask:0xf bank_mask:0xf
	global_load_dwordx4 v[120:123], v247, s[2:3] nt
	global_load_dwordx4 v[124:127], v247, s[2:3] offset:16 nt
	s_waitcnt vmcnt(30)
	v_fmac_f32_dpp v8, v240, v128 row_newbcast:12 row_mask:0xf bank_mask:0xf
	v_fmac_f32_dpp v9, v240, v129 row_newbcast:12 row_mask:0xf bank_mask:0xf
	v_fmac_f32_dpp v10, v240, v130 row_newbcast:12 row_mask:0xf bank_mask:0xf
	v_fmac_f32_dpp v11, v240, v131 row_newbcast:12 row_mask:0xf bank_mask:0xf
	v_fmac_f32_dpp v12, v240, v132 row_newbcast:12 row_mask:0xf bank_mask:0xf
	v_fmac_f32_dpp v13, v240, v133 row_newbcast:12 row_mask:0xf bank_mask:0xf
	v_fmac_f32_dpp v14, v240, v134 row_newbcast:12 row_mask:0xf bank_mask:0xf
	v_fmac_f32_dpp v15, v240, v135 row_newbcast:12 row_mask:0xf bank_mask:0xf
	global_load_dwordx4 v[128:131], v248, s[2:3] nt
	global_load_dwordx4 v[132:135], v248, s[2:3] offset:16 nt
	s_waitcnt vmcnt(30)
	v_fmac_f32_dpp v8, v240, v136 row_newbcast:13 row_mask:0xf bank_mask:0xf
	v_fmac_f32_dpp v9, v240, v137 row_newbcast:13 row_mask:0xf bank_mask:0xf
	v_fmac_f32_dpp v10, v240, v138 row_newbcast:13 row_mask:0xf bank_mask:0xf
	v_fmac_f32_dpp v11, v240, v139 row_newbcast:13 row_mask:0xf bank_mask:0xf
	v_fmac_f32_dpp v12, v240, v140 row_newbcast:13 row_mask:0xf bank_mask:0xf
	v_fmac_f32_dpp v13, v240, v141 row_newbcast:13 row_mask:0xf bank_mask:0xf
	v_fmac_f32_dpp v14, v240, v142 row_newbcast:13 row_mask:0xf bank_mask:0xf
	v_fmac_f32_dpp v15, v240, v143 row_newbcast:13 row_mask:0xf bank_mask:0xf
	global_load_dwordx4 v[136:139], v249, s[2:3] nt
	global_load_dwordx4 v[140:143], v249, s[2:3] offset:16 nt
	s_waitcnt vmcnt(30)
	v_fmac_f32_dpp v8, v240, v144 row_newbcast:14 row_mask:0xf bank_mask:0xf
	v_fmac_f32_dpp v9, v240, v145 row_newbcast:14 row_mask:0xf bank_mask:0xf
	v_fmac_f32_dpp v10, v240, v146 row_newbcast:14 row_mask:0xf bank_mask:0xf
	v_fmac_f32_dpp v11, v240, v147 row_newbcast:14 row_mask:0xf bank_mask:0xf
	v_fmac_f32_dpp v12, v240, v148 row_newbcast:14 row_mask:0xf bank_mask:0xf
	v_fmac_f32_dpp v13, v240, v149 row_newbcast:14 row_mask:0xf bank_mask:0xf
	v_fmac_f32_dpp v14, v240, v150 row_newbcast:14 row_mask:0xf bank_mask:0xf
	v_fmac_f32_dpp v15, v240, v151 row_newbcast:14 row_mask:0xf bank_mask:0xf
	global_load_dwordx4 v[144:147], v250, s[2:3] nt
	global_load_dwordx4 v[148:151], v250, s[2:3] offset:16 nt
	s_waitcnt vmcnt(30)
	v_fmac_f32_dpp v8, v240, v152 row_newbcast:15 row_mask:0xf bank_mask:0xf
	v_fmac_f32_dpp v9, v240, v153 row_newbcast:15 row_mask:0xf bank_mask:0xf
	v_fmac_f32_dpp v10, v240, v154 row_newbcast:15 row_mask:0xf bank_mask:0xf
	v_fmac_f32_dpp v11, v240, v155 row_newbcast:15 row_mask:0xf bank_mask:0xf
	v_fmac_f32_dpp v12, v240, v156 row_newbcast:15 row_mask:0xf bank_mask:0xf
	v_fmac_f32_dpp v13, v240, v157 row_newbcast:15 row_mask:0xf bank_mask:0xf
	v_fmac_f32_dpp v14, v240, v158 row_newbcast:15 row_mask:0xf bank_mask:0xf
	v_fmac_f32_dpp v15, v240, v159 row_newbcast:15 row_mask:0xf bank_mask:0xf
	global_load_dwordx4 v[152:155], v251, s[2:3] nt
	global_load_dwordx4 v[156:159], v251, s[2:3] offset:16 nt
	s_waitcnt vmcnt(30)
	v_mul_f32_e32 v160, v32, v0
	v_fmac_f32_e32 v160, v33, v1
	v_fmac_f32_e32 v160, v34, v2
	v_fmac_f32_e32 v160, v35, v3
	v_fmac_f32_e32 v160, v36, v4
	v_fmac_f32_e32 v160, v37, v5
	v_fmac_f32_e32 v160, v38, v6
	v_fmac_f32_e32 v160, v39, v7
	global_load_dwordx4 v[32:35], v24, s[4:5] nt
	global_load_dwordx4 v[36:39], v24, s[4:5] offset:16 nt
	s_waitcnt vmcnt(30)
	v_mul_f32_e32 v161, v40, v0
	v_fmac_f32_e32 v161, v41, v1
	v_fmac_f32_e32 v161, v42, v2
	v_fmac_f32_e32 v161, v43, v3
	v_fmac_f32_e32 v161, v44, v4
	v_fmac_f32_e32 v161, v45, v5
	v_fmac_f32_e32 v161, v46, v6
	v_fmac_f32_e32 v161, v47, v7
	global_load_dwordx4 v[40:43], v25, s[4:5] nt
	global_load_dwordx4 v[44:47], v25, s[4:5] offset:16 nt
	s_waitcnt vmcnt(30)
	v_mul_f32_e32 v162, v48, v0
	v_fmac_f32_e32 v162, v49, v1
	v_fmac_f32_e32 v162, v50, v2
	v_fmac_f32_e32 v162, v51, v3
	v_fmac_f32_e32 v162, v52, v4
	v_fmac_f32_e32 v162, v53, v5
	v_fmac_f32_e32 v162, v54, v6
	v_fmac_f32_e32 v162, v55, v7
	global_load_dwordx4 v[48:51], v26, s[4:5] nt
	global_load_dwordx4 v[52:55], v26, s[4:5] offset:16 nt
	s_waitcnt vmcnt(30)
	v_mul_f32_e32 v163, v56, v0
	v_fmac_f32_e32 v163, v57, v1
	v_fmac_f32_e32 v163, v58, v2
	v_fmac_f32_e32 v163, v59, v3
	v_fmac_f32_e32 v163, v60, v4
	v_fmac_f32_e32 v163, v61, v5
	v_fmac_f32_e32 v163, v62, v6
	v_fmac_f32_e32 v163, v63, v7
	global_load_dwordx4 v[56:59], v27, s[4:5] nt
	global_load_dwordx4 v[60:63], v27, s[4:5] offset:16 nt
	s_waitcnt vmcnt(30)
	v_mul_f32_e32 v164, v64, v0
	v_fmac_f32_e32 v164, v65, v1
	v_fmac_f32_e32 v164, v66, v2
	v_fmac_f32_e32 v164, v67, v3
	v_fmac_f32_e32 v164, v68, v4
	v_fmac_f32_e32 v164, v69, v5
	v_fmac_f32_e32 v164, v70, v6
	v_fmac_f32_e32 v164, v71, v7
	global_load_dwordx4 v[64:67], v28, s[4:5] nt
	global_load_dwordx4 v[68:71], v28, s[4:5] offset:16 nt
	s_waitcnt vmcnt(30)
	v_mul_f32_e32 v165, v72, v0
	v_fmac_f32_e32 v165, v73, v1
	v_fmac_f32_e32 v165, v74, v2
	v_fmac_f32_e32 v165, v75, v3
	v_fmac_f32_e32 v165, v76, v4
	v_fmac_f32_e32 v165, v77, v5
	v_fmac_f32_e32 v165, v78, v6
	v_fmac_f32_e32 v165, v79, v7
	global_load_dwordx4 v[72:75], v29, s[4:5] nt
	global_load_dwordx4 v[76:79], v29, s[4:5] offset:16 nt
	s_waitcnt vmcnt(30)
	v_mul_f32_e32 v166, v80, v0
	v_fmac_f32_e32 v166, v81, v1
	v_fmac_f32_e32 v166, v82, v2
	v_fmac_f32_e32 v166, v83, v3
	v_fmac_f32_e32 v166, v84, v4
	v_fmac_f32_e32 v166, v85, v5
	v_fmac_f32_e32 v166, v86, v6
	v_fmac_f32_e32 v166, v87, v7
	global_load_dwordx4 v[80:83], v30, s[4:5] nt
	global_load_dwordx4 v[84:87], v30, s[4:5] offset:16 nt
	s_waitcnt vmcnt(30)
	v_mul_f32_e32 v167, v88, v0
	v_fmac_f32_e32 v167, v89, v1
	v_fmac_f32_e32 v167, v90, v2
	v_fmac_f32_e32 v167, v91, v3
	v_fmac_f32_e32 v167, v92, v4
	v_fmac_f32_e32 v167, v93, v5
	v_fmac_f32_e32 v167, v94, v6
	v_fmac_f32_e32 v167, v95, v7
	global_load_dwordx4 v[88:91], v31, s[4:5] nt
	global_load_dwordx4 v[92:95], v31, s[4:5] offset:16 nt
	s_waitcnt vmcnt(30)
	v_mul_f32_e32 v168, v96, v0
	v_fmac_f32_e32 v168, v97, v1
	v_fmac_f32_e32 v168, v98, v2
	v_fmac_f32_e32 v168, v99, v3
	v_fmac_f32_e32 v168, v100, v4
	v_fmac_f32_e32 v168, v101, v5
	v_fmac_f32_e32 v168, v102, v6
	v_fmac_f32_e32 v168, v103, v7
	global_load_dwordx4 v[96:99], v244, s[4:5] nt
	global_load_dwordx4 v[100:103], v244, s[4:5] offset:16 nt
	s_waitcnt vmcnt(30)
	v_mul_f32_e32 v169, v104, v0
	v_fmac_f32_e32 v169, v105, v1
	v_fmac_f32_e32 v169, v106, v2
	v_fmac_f32_e32 v169, v107, v3
	v_fmac_f32_e32 v169, v108, v4
	v_fmac_f32_e32 v169, v109, v5
	v_fmac_f32_e32 v169, v110, v6
	v_fmac_f32_e32 v169, v111, v7
	global_load_dwordx4 v[104:107], v245, s[4:5] nt
	global_load_dwordx4 v[108:111], v245, s[4:5] offset:16 nt
	s_waitcnt vmcnt(30)
	v_mul_f32_e32 v170, v112, v0
	v_fmac_f32_e32 v170, v113, v1
	v_fmac_f32_e32 v170, v114, v2
	v_fmac_f32_e32 v170, v115, v3
	v_fmac_f32_e32 v170, v116, v4
	v_fmac_f32_e32 v170, v117, v5
	v_fmac_f32_e32 v170, v118, v6
	v_fmac_f32_e32 v170, v119, v7
	global_load_dwordx4 v[112:115], v246, s[4:5] nt
	global_load_dwordx4 v[116:119], v246, s[4:5] offset:16 nt
	s_waitcnt vmcnt(30)
	v_mul_f32_e32 v171, v120, v0
	v_fmac_f32_e32 v171, v121, v1
	v_fmac_f32_e32 v171, v122, v2
	v_fmac_f32_e32 v171, v123, v3
	v_fmac_f32_e32 v171, v124, v4
	v_fmac_f32_e32 v171, v125, v5
	v_fmac_f32_e32 v171, v126, v6
	v_fmac_f32_e32 v171, v127, v7
	global_load_dwordx4 v[120:123], v247, s[4:5] nt
	global_load_dwordx4 v[124:127], v247, s[4:5] offset:16 nt
	s_waitcnt vmcnt(30)
	v_mul_f32_e32 v172, v128, v0
	v_fmac_f32_e32 v172, v129, v1
	v_fmac_f32_e32 v172, v130, v2
	v_fmac_f32_e32 v172, v131, v3
	v_fmac_f32_e32 v172, v132, v4
	v_fmac_f32_e32 v172, v133, v5
	v_fmac_f32_e32 v172, v134, v6
	v_fmac_f32_e32 v172, v135, v7
	global_load_dwordx4 v[128:131], v248, s[4:5] nt
	global_load_dwordx4 v[132:135], v248, s[4:5] offset:16 nt
	s_waitcnt vmcnt(30)
	v_mul_f32_e32 v173, v136, v0
	v_fmac_f32_e32 v173, v137, v1
	v_fmac_f32_e32 v173, v138, v2
	v_fmac_f32_e32 v173, v139, v3
	v_fmac_f32_e32 v173, v140, v4
	v_fmac_f32_e32 v173, v141, v5
	v_fmac_f32_e32 v173, v142, v6
	v_fmac_f32_e32 v173, v143, v7
	global_load_dwordx4 v[136:139], v249, s[4:5] nt
	global_load_dwordx4 v[140:143], v249, s[4:5] offset:16 nt
	s_waitcnt vmcnt(30)
	v_mul_f32_e32 v174, v144, v0
	v_fmac_f32_e32 v174, v145, v1
	v_fmac_f32_e32 v174, v146, v2
	v_fmac_f32_e32 v174, v147, v3
	v_fmac_f32_e32 v174, v148, v4
	v_fmac_f32_e32 v174, v149, v5
	v_fmac_f32_e32 v174, v150, v6
	v_fmac_f32_e32 v174, v151, v7
	global_load_dwordx4 v[144:147], v250, s[4:5] nt
	global_load_dwordx4 v[148:151], v250, s[4:5] offset:16 nt
	s_waitcnt vmcnt(30)
	v_mul_f32_e32 v175, v152, v0
	v_fmac_f32_e32 v175, v153, v1
	v_fmac_f32_e32 v175, v154, v2
	v_fmac_f32_e32 v175, v155, v3
	v_fmac_f32_e32 v175, v156, v4
	v_fmac_f32_e32 v175, v157, v5
	v_fmac_f32_e32 v175, v158, v6
	v_fmac_f32_e32 v175, v159, v7
	global_load_dwordx4 v[152:155], v251, s[4:5] nt
	global_load_dwordx4 v[156:159], v251, s[4:5] offset:16 nt
	v_add_f32_dpp v160, v160, v160 row_ror:8 row_mask:0xf bank_mask:0x3
	v_add_f32_dpp v160, v168, v168 row_ror:8 row_mask:0xf bank_mask:0xc
	v_add_f32_dpp v161, v161, v161 row_ror:8 row_mask:0xf bank_mask:0x3
	v_add_f32_dpp v161, v169, v169 row_ror:8 row_mask:0xf bank_mask:0xc
	v_add_f32_dpp v162, v162, v162 row_ror:8 row_mask:0xf bank_mask:0x3
	v_add_f32_dpp v162, v170, v170 row_ror:8 row_mask:0xf bank_mask:0xc
	v_add_f32_dpp v163, v163, v163 row_ror:8 row_mask:0xf bank_mask:0x3
	v_add_f32_dpp v163, v171, v171 row_ror:8 row_mask:0xf bank_mask:0xc
	v_add_f32_dpp v164, v164, v164 row_ror:8 row_mask:0xf bank_mask:0x3
	v_add_f32_dpp v164, v172, v172 row_ror:8 row_mask:0xf bank_mask:0xc
	v_add_f32_dpp v165, v165, v165 row_ror:8 row_mask:0xf bank_mask:0x3
	v_add_f32_dpp v165, v173, v173 row_ror:8 row_mask:0xf bank_mask:0xc
	v_add_f32_dpp v166, v166, v166 row_ror:8 row_mask:0xf bank_mask:0x3
	v_add_f32_dpp v166, v174, v174 row_ror:8 row_mask:0xf bank_mask:0xc
	v_add_f32_dpp v167, v167, v167 row_ror:8 row_mask:0xf bank_mask:0x3
	v_add_f32_dpp v167, v175, v175 row_ror:8 row_mask:0xf bank_mask:0xc
	v_add_f32_dpp v160, v160, v160 row_shl:4 row_mask:0xf bank_mask:0x5
	v_add_f32_dpp v160, v164, v164 row_shr:4 row_mask:0xf bank_mask:0xa
	v_add_f32_dpp v161, v161, v161 row_shl:4 row_mask:0xf bank_mask:0x5
	v_add_f32_dpp v161, v165, v165 row_shr:4 row_mask:0xf bank_mask:0xa
	v_add_f32_dpp v162, v162, v162 row_shl:4 row_mask:0xf bank_mask:0x5
	v_add_f32_dpp v162, v166, v166 row_shr:4 row_mask:0xf bank_mask:0xa
	v_add_f32_dpp v163, v163, v163 row_shl:4 row_mask:0xf bank_mask:0x5
	v_add_f32_dpp v163, v167, v167 row_shr:4 row_mask:0xf bank_mask:0xa
	v_and_b32_e32 v176, 2, v18
	v_cmp_ne_u32_e32 vcc, 0, v176
	v_add_f32_dpp v230, v160, v160 quad_perm:[2,3,0,1] row_mask:0xf bank_mask:0xf
	v_add_f32_dpp v231, v162, v162 quad_perm:[2,3,0,1] row_mask:0xf bank_mask:0xf
	v_add_f32_dpp v232, v161, v161 quad_perm:[2,3,0,1] row_mask:0xf bank_mask:0xf
	v_add_f32_dpp v233, v163, v163 quad_perm:[2,3,0,1] row_mask:0xf bank_mask:0xf
	v_cndmask_b32_e32 v230, v230, v231, vcc
	v_cndmask_b32_e32 v232, v232, v233, vcc
	v_and_b32_e32 v176, 1, v18
	v_cmp_ne_u32_e32 vcc, 0, v176
	v_add_f32_dpp v231, v230, v230 quad_perm:[1,0,3,2] row_mask:0xf bank_mask:0xf
	v_add_f32_dpp v233, v232, v232 quad_perm:[1,0,3,2] row_mask:0xf bank_mask:0xf
	s_nop 1
	v_cndmask_b32_e32 v241, v231, v233, vcc
	s_nop 1
	v_max_f32_dpp v242, v241, v241 row_ror:8 row_mask:0xf bank_mask:0xf
	s_nop 1
	v_max_f32_dpp v242, v242, v242 row_ror:4 row_mask:0xf bank_mask:0xf
	s_nop 1
	v_max_f32_dpp v242, v242, v242 row_ror:2 row_mask:0xf bank_mask:0xf
	s_nop 1
	v_max_f32_dpp v242, v242, v242 row_ror:1 row_mask:0xf bank_mask:0xf
	ds_bpermute_b32 v234, v238, v242
	s_waitcnt lgkmcnt(0)
	v_max_f32_e32 v242, v242, v234
	ds_bpermute_b32 v234, v239, v242
	s_waitcnt lgkmcnt(0)
	v_max_f32_e32 v242, v242, v234
	v_max_f32_e32 v242, v16, v242
	v_sub_f32_e32 v243, v16, v242
	v_sub_f32_e32 v240, v241, v242
	v_mul_f32_e32 v243, 0x3fb8aa3b, v243
	v_mul_f32_e32 v240, 0x3fb8aa3b, v240
	v_exp_f32_e32 v243, v243
	v_exp_f32_e32 v240, v240
	v_mov_b32_e32 v16, v242
	s_nop 0
	s_nop 1
	v_add_f32_dpp v235, v240, v240 row_ror:8 row_mask:0xf bank_mask:0xf
	s_nop 1
	v_add_f32_dpp v235, v235, v235 row_ror:4 row_mask:0xf bank_mask:0xf
	s_nop 1
	v_add_f32_dpp v235, v235, v235 row_ror:2 row_mask:0xf bank_mask:0xf
	s_nop 1
	v_add_f32_dpp v235, v235, v235 row_ror:1 row_mask:0xf bank_mask:0xf
	ds_bpermute_b32 v234, v238, v235
	s_waitcnt lgkmcnt(0)
	v_add_f32_e32 v235, v235, v234
	ds_bpermute_b32 v234, v239, v235
	s_waitcnt lgkmcnt(0)
	v_add_f32_e32 v235, v235, v234
	v_fma_f32 v17, v17, v243, v235
	v_mul_f32_e32 v8, v8, v243
	v_mul_f32_e32 v9, v9, v243
	v_mul_f32_e32 v10, v10, v243
	v_mul_f32_e32 v11, v11, v243
	v_mul_f32_e32 v12, v12, v243
	v_mul_f32_e32 v13, v13, v243
	v_mul_f32_e32 v14, v14, v243
	v_mul_f32_e32 v15, v15, v243
	s_waitcnt vmcnt(30)
	v_fmac_f32_dpp v8, v240, v32 row_newbcast:0 row_mask:0xf bank_mask:0xf
	v_fmac_f32_dpp v9, v240, v33 row_newbcast:0 row_mask:0xf bank_mask:0xf
	v_fmac_f32_dpp v10, v240, v34 row_newbcast:0 row_mask:0xf bank_mask:0xf
	v_fmac_f32_dpp v11, v240, v35 row_newbcast:0 row_mask:0xf bank_mask:0xf
	v_fmac_f32_dpp v12, v240, v36 row_newbcast:0 row_mask:0xf bank_mask:0xf
	v_fmac_f32_dpp v13, v240, v37 row_newbcast:0 row_mask:0xf bank_mask:0xf
	v_fmac_f32_dpp v14, v240, v38 row_newbcast:0 row_mask:0xf bank_mask:0xf
	v_fmac_f32_dpp v15, v240, v39 row_newbcast:0 row_mask:0xf bank_mask:0xf
	s_waitcnt vmcnt(28)
	v_fmac_f32_dpp v8, v240, v40 row_newbcast:1 row_mask:0xf bank_mask:0xf
	v_fmac_f32_dpp v9, v240, v41 row_newbcast:1 row_mask:0xf bank_mask:0xf
	v_fmac_f32_dpp v10, v240, v42 row_newbcast:1 row_mask:0xf bank_mask:0xf
	v_fmac_f32_dpp v11, v240, v43 row_newbcast:1 row_mask:0xf bank_mask:0xf
	v_fmac_f32_dpp v12, v240, v44 row_newbcast:1 row_mask:0xf bank_mask:0xf
	v_fmac_f32_dpp v13, v240, v45 row_newbcast:1 row_mask:0xf bank_mask:0xf
	v_fmac_f32_dpp v14, v240, v46 row_newbcast:1 row_mask:0xf bank_mask:0xf
	v_fmac_f32_dpp v15, v240, v47 row_newbcast:1 row_mask:0xf bank_mask:0xf
	s_waitcnt vmcnt(26)
	v_fmac_f32_dpp v8, v240, v48 row_newbcast:2 row_mask:0xf bank_mask:0xf
	v_fmac_f32_dpp v9, v240, v49 row_newbcast:2 row_mask:0xf bank_mask:0xf
	v_fmac_f32_dpp v10, v240, v50 row_newbcast:2 row_mask:0xf bank_mask:0xf
	v_fmac_f32_dpp v11, v240, v51 row_newbcast:2 row_mask:0xf bank_mask:0xf
	v_fmac_f32_dpp v12, v240, v52 row_newbcast:2 row_mask:0xf bank_mask:0xf
	v_fmac_f32_dpp v13, v240, v53 row_newbcast:2 row_mask:0xf bank_mask:0xf
	v_fmac_f32_dpp v14, v240, v54 row_newbcast:2 row_mask:0xf bank_mask:0xf
	v_fmac_f32_dpp v15, v240, v55 row_newbcast:2 row_mask:0xf bank_mask:0xf
	s_waitcnt vmcnt(24)
	v_fmac_f32_dpp v8, v240, v56 row_newbcast:3 row_mask:0xf bank_mask:0xf
	v_fmac_f32_dpp v9, v240, v57 row_newbcast:3 row_mask:0xf bank_mask:0xf
	v_fmac_f32_dpp v10, v240, v58 row_newbcast:3 row_mask:0xf bank_mask:0xf
	v_fmac_f32_dpp v11, v240, v59 row_newbcast:3 row_mask:0xf bank_mask:0xf
	v_fmac_f32_dpp v12, v240, v60 row_newbcast:3 row_mask:0xf bank_mask:0xf
	v_fmac_f32_dpp v13, v240, v61 row_newbcast:3 row_mask:0xf bank_mask:0xf
	v_fmac_f32_dpp v14, v240, v62 row_newbcast:3 row_mask:0xf bank_mask:0xf
	v_fmac_f32_dpp v15, v240, v63 row_newbcast:3 row_mask:0xf bank_mask:0xf
	s_waitcnt vmcnt(22)
	v_fmac_f32_dpp v8, v240, v64 row_newbcast:4 row_mask:0xf bank_mask:0xf
	v_fmac_f32_dpp v9, v240, v65 row_newbcast:4 row_mask:0xf bank_mask:0xf
	v_fmac_f32_dpp v10, v240, v66 row_newbcast:4 row_mask:0xf bank_mask:0xf
	v_fmac_f32_dpp v11, v240, v67 row_newbcast:4 row_mask:0xf bank_mask:0xf
	v_fmac_f32_dpp v12, v240, v68 row_newbcast:4 row_mask:0xf bank_mask:0xf
	v_fmac_f32_dpp v13, v240, v69 row_newbcast:4 row_mask:0xf bank_mask:0xf
	v_fmac_f32_dpp v14, v240, v70 row_newbcast:4 row_mask:0xf bank_mask:0xf
	v_fmac_f32_dpp v15, v240, v71 row_newbcast:4 row_mask:0xf bank_mask:0xf
	s_waitcnt vmcnt(20)
	v_fmac_f32_dpp v8, v240, v72 row_newbcast:5 row_mask:0xf bank_mask:0xf
	v_fmac_f32_dpp v9, v240, v73 row_newbcast:5 row_mask:0xf bank_mask:0xf
	v_fmac_f32_dpp v10, v240, v74 row_newbcast:5 row_mask:0xf bank_mask:0xf
	v_fmac_f32_dpp v11, v240, v75 row_newbcast:5 row_mask:0xf bank_mask:0xf
	v_fmac_f32_dpp v12, v240, v76 row_newbcast:5 row_mask:0xf bank_mask:0xf
	v_fmac_f32_dpp v13, v240, v77 row_newbcast:5 row_mask:0xf bank_mask:0xf
	v_fmac_f32_dpp v14, v240, v78 row_newbcast:5 row_mask:0xf bank_mask:0xf
	v_fmac_f32_dpp v15, v240, v79 row_newbcast:5 row_mask:0xf bank_mask:0xf
	s_waitcnt vmcnt(18)
	v_fmac_f32_dpp v8, v240, v80 row_newbcast:6 row_mask:0xf bank_mask:0xf
	v_fmac_f32_dpp v9, v240, v81 row_newbcast:6 row_mask:0xf bank_mask:0xf
	v_fmac_f32_dpp v10, v240, v82 row_newbcast:6 row_mask:0xf bank_mask:0xf
	v_fmac_f32_dpp v11, v240, v83 row_newbcast:6 row_mask:0xf bank_mask:0xf
	v_fmac_f32_dpp v12, v240, v84 row_newbcast:6 row_mask:0xf bank_mask:0xf
	v_fmac_f32_dpp v13, v240, v85 row_newbcast:6 row_mask:0xf bank_mask:0xf
	v_fmac_f32_dpp v14, v240, v86 row_newbcast:6 row_mask:0xf bank_mask:0xf
	v_fmac_f32_dpp v15, v240, v87 row_newbcast:6 row_mask:0xf bank_mask:0xf
	s_waitcnt vmcnt(16)
	v_fmac_f32_dpp v8, v240, v88 row_newbcast:7 row_mask:0xf bank_mask:0xf
	v_fmac_f32_dpp v9, v240, v89 row_newbcast:7 row_mask:0xf bank_mask:0xf
	v_fmac_f32_dpp v10, v240, v90 row_newbcast:7 row_mask:0xf bank_mask:0xf
	v_fmac_f32_dpp v11, v240, v91 row_newbcast:7 row_mask:0xf bank_mask:0xf
	v_fmac_f32_dpp v12, v240, v92 row_newbcast:7 row_mask:0xf bank_mask:0xf
	v_fmac_f32_dpp v13, v240, v93 row_newbcast:7 row_mask:0xf bank_mask:0xf
	v_fmac_f32_dpp v14, v240, v94 row_newbcast:7 row_mask:0xf bank_mask:0xf
	v_fmac_f32_dpp v15, v240, v95 row_newbcast:7 row_mask:0xf bank_mask:0xf
	s_waitcnt vmcnt(14)
	v_fmac_f32_dpp v8, v240, v96 row_newbcast:8 row_mask:0xf bank_mask:0xf
	v_fmac_f32_dpp v9, v240, v97 row_newbcast:8 row_mask:0xf bank_mask:0xf
	v_fmac_f32_dpp v10, v240, v98 row_newbcast:8 row_mask:0xf bank_mask:0xf
	v_fmac_f32_dpp v11, v240, v99 row_newbcast:8 row_mask:0xf bank_mask:0xf
	v_fmac_f32_dpp v12, v240, v100 row_newbcast:8 row_mask:0xf bank_mask:0xf
	v_fmac_f32_dpp v13, v240, v101 row_newbcast:8 row_mask:0xf bank_mask:0xf
	v_fmac_f32_dpp v14, v240, v102 row_newbcast:8 row_mask:0xf bank_mask:0xf
	v_fmac_f32_dpp v15, v240, v103 row_newbcast:8 row_mask:0xf bank_mask:0xf
	s_waitcnt vmcnt(12)
	v_fmac_f32_dpp v8, v240, v104 row_newbcast:9 row_mask:0xf bank_mask:0xf
	v_fmac_f32_dpp v9, v240, v105 row_newbcast:9 row_mask:0xf bank_mask:0xf
	v_fmac_f32_dpp v10, v240, v106 row_newbcast:9 row_mask:0xf bank_mask:0xf
	v_fmac_f32_dpp v11, v240, v107 row_newbcast:9 row_mask:0xf bank_mask:0xf
	v_fmac_f32_dpp v12, v240, v108 row_newbcast:9 row_mask:0xf bank_mask:0xf
	v_fmac_f32_dpp v13, v240, v109 row_newbcast:9 row_mask:0xf bank_mask:0xf
	v_fmac_f32_dpp v14, v240, v110 row_newbcast:9 row_mask:0xf bank_mask:0xf
	v_fmac_f32_dpp v15, v240, v111 row_newbcast:9 row_mask:0xf bank_mask:0xf
	s_waitcnt vmcnt(10)
	v_fmac_f32_dpp v8, v240, v112 row_newbcast:10 row_mask:0xf bank_mask:0xf
	v_fmac_f32_dpp v9, v240, v113 row_newbcast:10 row_mask:0xf bank_mask:0xf
	v_fmac_f32_dpp v10, v240, v114 row_newbcast:10 row_mask:0xf bank_mask:0xf
	v_fmac_f32_dpp v11, v240, v115 row_newbcast:10 row_mask:0xf bank_mask:0xf
	v_fmac_f32_dpp v12, v240, v116 row_newbcast:10 row_mask:0xf bank_mask:0xf
	v_fmac_f32_dpp v13, v240, v117 row_newbcast:10 row_mask:0xf bank_mask:0xf
	v_fmac_f32_dpp v14, v240, v118 row_newbcast:10 row_mask:0xf bank_mask:0xf
	v_fmac_f32_dpp v15, v240, v119 row_newbcast:10 row_mask:0xf bank_mask:0xf
	s_waitcnt vmcnt(8)
	v_fmac_f32_dpp v8, v240, v120 row_newbcast:11 row_mask:0xf bank_mask:0xf
	v_fmac_f32_dpp v9, v240, v121 row_newbcast:11 row_mask:0xf bank_mask:0xf
	v_fmac_f32_dpp v10, v240, v122 row_newbcast:11 row_mask:0xf bank_mask:0xf
	v_fmac_f32_dpp v11, v240, v123 row_newbcast:11 row_mask:0xf bank_mask:0xf
	v_fmac_f32_dpp v12, v240, v124 row_newbcast:11 row_mask:0xf bank_mask:0xf
	v_fmac_f32_dpp v13, v240, v125 row_newbcast:11 row_mask:0xf bank_mask:0xf
	v_fmac_f32_dpp v14, v240, v126 row_newbcast:11 row_mask:0xf bank_mask:0xf
	v_fmac_f32_dpp v15, v240, v127 row_newbcast:11 row_mask:0xf bank_mask:0xf
	s_waitcnt vmcnt(6)
	v_fmac_f32_dpp v8, v240, v128 row_newbcast:12 row_mask:0xf bank_mask:0xf
	v_fmac_f32_dpp v9, v240, v129 row_newbcast:12 row_mask:0xf bank_mask:0xf
	v_fmac_f32_dpp v10, v240, v130 row_newbcast:12 row_mask:0xf bank_mask:0xf
	v_fmac_f32_dpp v11, v240, v131 row_newbcast:12 row_mask:0xf bank_mask:0xf
	v_fmac_f32_dpp v12, v240, v132 row_newbcast:12 row_mask:0xf bank_mask:0xf
	v_fmac_f32_dpp v13, v240, v133 row_newbcast:12 row_mask:0xf bank_mask:0xf
	v_fmac_f32_dpp v14, v240, v134 row_newbcast:12 row_mask:0xf bank_mask:0xf
	v_fmac_f32_dpp v15, v240, v135 row_newbcast:12 row_mask:0xf bank_mask:0xf
	s_waitcnt vmcnt(4)
	v_fmac_f32_dpp v8, v240, v136 row_newbcast:13 row_mask:0xf bank_mask:0xf
	v_fmac_f32_dpp v9, v240, v137 row_newbcast:13 row_mask:0xf bank_mask:0xf
	v_fmac_f32_dpp v10, v240, v138 row_newbcast:13 row_mask:0xf bank_mask:0xf
	v_fmac_f32_dpp v11, v240, v139 row_newbcast:13 row_mask:0xf bank_mask:0xf
	v_fmac_f32_dpp v12, v240, v140 row_newbcast:13 row_mask:0xf bank_mask:0xf
	v_fmac_f32_dpp v13, v240, v141 row_newbcast:13 row_mask:0xf bank_mask:0xf
	v_fmac_f32_dpp v14, v240, v142 row_newbcast:13 row_mask:0xf bank_mask:0xf
	v_fmac_f32_dpp v15, v240, v143 row_newbcast:13 row_mask:0xf bank_mask:0xf
	s_waitcnt vmcnt(2)
	v_fmac_f32_dpp v8, v240, v144 row_newbcast:14 row_mask:0xf bank_mask:0xf
	v_fmac_f32_dpp v9, v240, v145 row_newbcast:14 row_mask:0xf bank_mask:0xf
	v_fmac_f32_dpp v10, v240, v146 row_newbcast:14 row_mask:0xf bank_mask:0xf
	v_fmac_f32_dpp v11, v240, v147 row_newbcast:14 row_mask:0xf bank_mask:0xf
	v_fmac_f32_dpp v12, v240, v148 row_newbcast:14 row_mask:0xf bank_mask:0xf
	v_fmac_f32_dpp v13, v240, v149 row_newbcast:14 row_mask:0xf bank_mask:0xf
	v_fmac_f32_dpp v14, v240, v150 row_newbcast:14 row_mask:0xf bank_mask:0xf
	v_fmac_f32_dpp v15, v240, v151 row_newbcast:14 row_mask:0xf bank_mask:0xf
	s_waitcnt vmcnt(0)
	v_fmac_f32_dpp v8, v240, v152 row_newbcast:15 row_mask:0xf bank_mask:0xf
	v_fmac_f32_dpp v9, v240, v153 row_newbcast:15 row_mask:0xf bank_mask:0xf
	v_fmac_f32_dpp v10, v240, v154 row_newbcast:15 row_mask:0xf bank_mask:0xf
	v_fmac_f32_dpp v11, v240, v155 row_newbcast:15 row_mask:0xf bank_mask:0xf
	v_fmac_f32_dpp v12, v240, v156 row_newbcast:15 row_mask:0xf bank_mask:0xf
	v_fmac_f32_dpp v13, v240, v157 row_newbcast:15 row_mask:0xf bank_mask:0xf
	v_fmac_f32_dpp v14, v240, v158 row_newbcast:15 row_mask:0xf bank_mask:0xf
	v_fmac_f32_dpp v15, v240, v159 row_newbcast:15 row_mask:0xf bank_mask:0xf
	s_lshl_b32 s29, s10, 12
	v_lshlrev_b32_e32 v236, 5, v22
	v_add_u32_e32 v236, s29, v236
	global_load_dwordx4 v[32:35], v236, s[20:21]
	global_load_dwordx4 v[36:39], v236, s[20:21] offset:16
	global_load_dwordx4 v[40:43], v236, s[22:23]
	global_load_dwordx4 v[44:47], v236, s[22:23] offset:16
	ds_bpermute_b32 v160, v238, v8
	ds_bpermute_b32 v161, v238, v9
	ds_bpermute_b32 v162, v238, v10
	ds_bpermute_b32 v163, v238, v11
	ds_bpermute_b32 v164, v238, v12
	ds_bpermute_b32 v165, v238, v13
	ds_bpermute_b32 v166, v238, v14
	ds_bpermute_b32 v167, v238, v15
	s_waitcnt lgkmcnt(0)
	v_add_f32_e32 v8, v8, v160
	v_add_f32_e32 v9, v9, v161
	v_add_f32_e32 v10, v10, v162
	v_add_f32_e32 v11, v11, v163
	v_add_f32_e32 v12, v12, v164
	v_add_f32_e32 v13, v13, v165
	v_add_f32_e32 v14, v14, v166
	v_add_f32_e32 v15, v15, v167
	ds_bpermute_b32 v160, v239, v8
	ds_bpermute_b32 v161, v239, v9
	ds_bpermute_b32 v162, v239, v10
	ds_bpermute_b32 v163, v239, v11
	ds_bpermute_b32 v164, v239, v12
	ds_bpermute_b32 v165, v239, v13
	ds_bpermute_b32 v166, v239, v14
	ds_bpermute_b32 v167, v239, v15
	s_waitcnt lgkmcnt(0)
	v_add_f32_e32 v8, v8, v160
	v_add_f32_e32 v9, v9, v161
	v_add_f32_e32 v10, v10, v162
	v_add_f32_e32 v11, v11, v163
	v_add_f32_e32 v12, v12, v164
	v_add_f32_e32 v13, v13, v165
	v_add_f32_e32 v14, v14, v166
	v_add_f32_e32 v15, v15, v167
	s_waitcnt vmcnt(0)
	s_cmp_lg_u32 s11, 0
	s_cbranch_scc1 .Lsd_noself13
	v_mul_f32_e32 v241, v32, v0
	v_fmac_f32_e32 v241, v33, v1
	v_fmac_f32_e32 v241, v34, v2
	v_fmac_f32_e32 v241, v35, v3
	v_fmac_f32_e32 v241, v36, v4
	v_fmac_f32_e32 v241, v37, v5
	v_fmac_f32_e32 v241, v38, v6
	v_fmac_f32_e32 v241, v39, v7
	s_nop 1
	v_add_f32_dpp v241, v241, v241 row_ror:8 row_mask:0xf bank_mask:0xf
	s_nop 1
	v_add_f32_dpp v241, v241, v241 row_ror:4 row_mask:0xf bank_mask:0xf
	s_nop 1
	v_add_f32_dpp v241, v241, v241 row_ror:2 row_mask:0xf bank_mask:0xf
	s_nop 1
	v_add_f32_dpp v241, v241, v241 row_ror:1 row_mask:0xf bank_mask:0xf
	v_max_f32_e32 v242, v16, v241
	v_sub_f32_e32 v243, v16, v242
	v_sub_f32_e32 v240, v241, v242
	v_mul_f32_e32 v243, 0x3fb8aa3b, v243
	v_mul_f32_e32 v240, 0x3fb8aa3b, v240
	v_exp_f32_e32 v243, v243
	v_exp_f32_e32 v240, v240
	v_mov_b32_e32 v16, v242
	v_mul_f32_e32 v240, 0x40400000, v240
	v_fma_f32 v17, v17, v243, v240
	v_mul_f32_e32 v8, v8, v243
	v_fmac_f32_e32 v8, v240, v40
	v_mul_f32_e32 v9, v9, v243
	v_fmac_f32_e32 v9, v240, v41
	v_mul_f32_e32 v10, v10, v243
	v_fmac_f32_e32 v10, v240, v42
	v_mul_f32_e32 v11, v11, v243
	v_fmac_f32_e32 v11, v240, v43
	v_mul_f32_e32 v12, v12, v243
	v_fmac_f32_e32 v12, v240, v44
	v_mul_f32_e32 v13, v13, v243
	v_fmac_f32_e32 v13, v240, v45
	v_mul_f32_e32 v14, v14, v243
	v_fmac_f32_e32 v14, v240, v46
	v_mul_f32_e32 v15, v15, v243
	v_fmac_f32_e32 v15, v240, v47
